# MFMA order within each phase: weight-fragment operand held for 4 consecutive MFMAs (snake), on top of combo4
# speedup vs baseline: 1.0020x; 1.0020x over previous
.LBB0_175:
	s_add_i32 s29, s29, 2
	s_mov_b32 s44, s29
	s_ashr_i32 s45, s44, 31
	s_lshl_b64 s[82:83], s[44:45], 7
	s_add_u32 s45, s82, 0x100
	s_addc_u32 s81, s83, 0
	s_add_u32 s84, s42, s45
	s_addc_u32 s85, s43, s81
	s_add_u32 s86, s40, s45
	s_addc_u32 s81, s41, s81
	s_cmp_eq_u32 s44, 14
	s_cselect_b32 s45, s75, s85
	s_cselect_b32 s44, s76, s84
	s_cselect_b32 s85, s31, s81
	s_cselect_b32 s84, s74, s86
	s_add_u32 s82, s42, s82
	s_addc_u32 s83, s43, s83
	v_lshl_add_u64 v[212:213], s[82:83], 0, v[130:131]
	s_mov_b32 m0, s66
	v_lshl_add_u64 v[214:215], v[212:213], 0, s[22:23]
	global_load_lds_dwordx4 v[214:215], off
	v_lshl_add_u64 v[212:213], v[212:213], 0, s[24:25]
	s_mov_b32 m0, s67
	s_nop 0
	global_load_lds_dwordx4 v[212:213], off
	ds_read_b128 v[146:149], v141
	ds_read_b128 v[150:153], v141 offset:1024
	ds_read_b128 v[154:157], v141 offset:2048
	ds_read_b128 v[158:161], v141 offset:3072
	ds_read_b128 v[162:165], v142
	ds_read_b128 v[166:169], v142 offset:1024
	ds_read_b128 v[170:173], v142 offset:2048
	ds_read_b128 v[174:177], v142 offset:3072
	ds_read_b128 v[178:181], v143
	ds_read_b128 v[182:185], v143 offset:1024
	ds_read_b128 v[186:189], v143 offset:2048
	ds_read_b128 v[190:193], v143 offset:3072
	ds_read_b128 v[194:197], v143 offset:4096
	ds_read_b128 v[198:201], v143 offset:5120
	ds_read_b128 v[202:205], v143 offset:6144
	ds_read_b128 v[206:209], v143 offset:7168
	s_waitcnt vmcnt(8)
	s_waitcnt lgkmcnt(0)
	s_barrier
	s_waitcnt lgkmcnt(0)
	v_mfma_f32_16x16x32_bf16 v[124:127], v[146:149], v[178:181], v[124:127]
	v_mfma_f32_16x16x32_bf16 v[108:111], v[146:149], v[186:189], v[108:111]
	v_mfma_f32_16x16x32_bf16 v[92:95], v[146:149], v[194:197], v[92:95]
	v_mfma_f32_16x16x32_bf16 v[76:79], v[146:149], v[202:205], v[76:79]
	v_mfma_f32_16x16x32_bf16 v[64:67], v[154:157], v[202:205], v[64:67]
	v_mfma_f32_16x16x32_bf16 v[80:83], v[154:157], v[194:197], v[80:83]
	v_mfma_f32_16x16x32_bf16 v[96:99], v[154:157], v[186:189], v[96:99]
	v_mfma_f32_16x16x32_bf16 v[112:115], v[154:157], v[178:181], v[112:115]
	v_mfma_f32_16x16x32_bf16 v[120:123], v[162:165], v[178:181], v[120:123]
	v_mfma_f32_16x16x32_bf16 v[104:107], v[162:165], v[186:189], v[104:107]
	v_mfma_f32_16x16x32_bf16 v[88:91], v[162:165], v[194:197], v[88:91]
	v_mfma_f32_16x16x32_bf16 v[72:75], v[162:165], v[202:205], v[72:75]
	v_mfma_f32_16x16x32_bf16 v[68:71], v[170:173], v[202:205], v[68:71]
	v_mfma_f32_16x16x32_bf16 v[84:87], v[170:173], v[194:197], v[84:87]
	v_mfma_f32_16x16x32_bf16 v[100:103], v[170:173], v[186:189], v[100:103]
	v_mfma_f32_16x16x32_bf16 v[116:119], v[170:173], v[178:181], v[116:119]
	v_mfma_f32_16x16x32_bf16 v[124:127], v[150:153], v[182:185], v[124:127]
	v_mfma_f32_16x16x32_bf16 v[108:111], v[150:153], v[190:193], v[108:111]
	v_mfma_f32_16x16x32_bf16 v[92:95], v[150:153], v[198:201], v[92:95]
	v_mfma_f32_16x16x32_bf16 v[76:79], v[150:153], v[206:209], v[76:79]
	v_mfma_f32_16x16x32_bf16 v[64:67], v[158:161], v[206:209], v[64:67]
	v_mfma_f32_16x16x32_bf16 v[80:83], v[158:161], v[198:201], v[80:83]
	v_mfma_f32_16x16x32_bf16 v[96:99], v[158:161], v[190:193], v[96:99]
	v_mfma_f32_16x16x32_bf16 v[112:115], v[158:161], v[182:185], v[112:115]
	v_mfma_f32_16x16x32_bf16 v[120:123], v[166:169], v[182:185], v[120:123]
	v_mfma_f32_16x16x32_bf16 v[104:107], v[166:169], v[190:193], v[104:107]
	v_mfma_f32_16x16x32_bf16 v[88:91], v[166:169], v[198:201], v[88:91]
	v_mfma_f32_16x16x32_bf16 v[72:75], v[166:169], v[206:209], v[72:75]
	v_mfma_f32_16x16x32_bf16 v[68:71], v[174:177], v[206:209], v[68:71]
	v_mfma_f32_16x16x32_bf16 v[84:87], v[174:177], v[198:201], v[84:87]
	v_mfma_f32_16x16x32_bf16 v[100:103], v[174:177], v[190:193], v[100:103]
	v_mfma_f32_16x16x32_bf16 v[116:119], v[174:177], v[182:185], v[116:119]
	s_barrier
	s_mov_b32 m0, s68
	v_lshl_add_u64 v[212:213], s[84:85], 0, v[128:129]
	global_load_lds_dwordx4 v[212:213], off
	v_lshl_add_u64 v[214:215], v[212:213], 0, s[0:1]
	s_mov_b32 m0, s69
	s_nop 0
	global_load_lds_dwordx4 v[214:215], off
	v_lshl_add_u64 v[214:215], v[212:213], 0, s[2:3]
	s_mov_b32 m0, s70
	s_nop 0
	global_load_lds_dwordx4 v[214:215], off
	v_lshl_add_u64 v[214:215], v[212:213], 0, s[8:9]
	s_mov_b32 m0, s71
	s_nop 0
	global_load_lds_dwordx4 v[214:215], off
	v_lshl_add_u64 v[214:215], s[44:45], 0, v[130:131]
	s_mov_b32 m0, s39
	v_lshl_add_u64 v[216:217], v[214:215], 0, s[0:1]
	global_load_lds_dwordx4 v[214:215], off
	s_mov_b32 m0, s56
	s_nop 0
	global_load_lds_dwordx4 v[216:217], off
	ds_read_b128 v[178:181], v143 offset:16384
	ds_read_b128 v[182:185], v143 offset:17408
	ds_read_b128 v[186:189], v143 offset:18432
	ds_read_b128 v[190:193], v143 offset:19456
	ds_read_b128 v[194:197], v143 offset:20480
	ds_read_b128 v[198:201], v143 offset:21504
	ds_read_b128 v[202:205], v143 offset:22528
	ds_read_b128 v[206:209], v143 offset:23552
	s_waitcnt vmcnt(8)
	s_waitcnt lgkmcnt(0)
	s_barrier
	s_waitcnt lgkmcnt(0)
	v_mfma_f32_16x16x32_bf16 v[60:63], v[146:149], v[178:181], v[60:63]
	v_mfma_f32_16x16x32_bf16 v[44:47], v[146:149], v[186:189], v[44:47]
	v_mfma_f32_16x16x32_bf16 v[28:31], v[146:149], v[194:197], v[28:31]
	v_mfma_f32_16x16x32_bf16 v[12:15], v[146:149], v[202:205], v[12:15]
	v_mfma_f32_16x16x32_bf16 v[0:3], v[154:157], v[202:205], v[0:3]
	v_mfma_f32_16x16x32_bf16 v[16:19], v[154:157], v[194:197], v[16:19]
	v_mfma_f32_16x16x32_bf16 v[32:35], v[154:157], v[186:189], v[32:35]
	v_mfma_f32_16x16x32_bf16 v[48:51], v[154:157], v[178:181], v[48:51]
	v_mfma_f32_16x16x32_bf16 v[56:59], v[162:165], v[178:181], v[56:59]
	v_mfma_f32_16x16x32_bf16 v[40:43], v[162:165], v[186:189], v[40:43]
	v_mfma_f32_16x16x32_bf16 v[24:27], v[162:165], v[194:197], v[24:27]
	v_mfma_f32_16x16x32_bf16 v[8:11], v[162:165], v[202:205], v[8:11]
	v_mfma_f32_16x16x32_bf16 v[4:7], v[170:173], v[202:205], v[4:7]
	v_mfma_f32_16x16x32_bf16 v[20:23], v[170:173], v[194:197], v[20:23]
	v_mfma_f32_16x16x32_bf16 v[36:39], v[170:173], v[186:189], v[36:39]
	v_mfma_f32_16x16x32_bf16 v[52:55], v[170:173], v[178:181], v[52:55]
	v_mfma_f32_16x16x32_bf16 v[60:63], v[150:153], v[182:185], v[60:63]
	v_mfma_f32_16x16x32_bf16 v[44:47], v[150:153], v[190:193], v[44:47]
	v_mfma_f32_16x16x32_bf16 v[28:31], v[150:153], v[198:201], v[28:31]
	v_mfma_f32_16x16x32_bf16 v[12:15], v[150:153], v[206:209], v[12:15]
	v_mfma_f32_16x16x32_bf16 v[0:3], v[158:161], v[206:209], v[0:3]
	v_mfma_f32_16x16x32_bf16 v[16:19], v[158:161], v[198:201], v[16:19]
	v_mfma_f32_16x16x32_bf16 v[32:35], v[158:161], v[190:193], v[32:35]
	v_mfma_f32_16x16x32_bf16 v[48:51], v[158:161], v[182:185], v[48:51]
	v_mfma_f32_16x16x32_bf16 v[56:59], v[166:169], v[182:185], v[56:59]
	v_mfma_f32_16x16x32_bf16 v[40:43], v[166:169], v[190:193], v[40:43]
	v_mfma_f32_16x16x32_bf16 v[24:27], v[166:169], v[198:201], v[24:27]
	v_mfma_f32_16x16x32_bf16 v[8:11], v[166:169], v[206:209], v[8:11]
	v_mfma_f32_16x16x32_bf16 v[4:7], v[174:177], v[206:209], v[4:7]
	v_mfma_f32_16x16x32_bf16 v[20:23], v[174:177], v[198:201], v[20:23]
	v_mfma_f32_16x16x32_bf16 v[36:39], v[174:177], v[190:193], v[36:39]
	v_mfma_f32_16x16x32_bf16 v[52:55], v[174:177], v[182:185], v[52:55]
	s_barrier
	s_mov_b32 m0, s57
	v_lshl_add_u64 v[216:217], v[214:215], 0, s[2:3]
	global_load_lds_dwordx4 v[216:217], off
	v_lshl_add_u64 v[216:217], v[214:215], 0, s[8:9]
	s_mov_b32 m0, s58
	s_nop 0
	global_load_lds_dwordx4 v[216:217], off
	ds_read_b128 v[146:149], v144
	ds_read_b128 v[150:153], v144 offset:1024
	ds_read_b128 v[154:157], v144 offset:2048
	ds_read_b128 v[158:161], v144 offset:3072
	ds_read_b128 v[162:165], v136
	ds_read_b128 v[166:169], v136 offset:1024
	ds_read_b128 v[170:173], v136 offset:2048
	ds_read_b128 v[174:177], v136 offset:3072
	ds_read_b128 v[178:181], v143 offset:32768
	ds_read_b128 v[182:185], v143 offset:33792
	ds_read_b128 v[186:189], v143 offset:34816
	ds_read_b128 v[190:193], v143 offset:35840
	ds_read_b128 v[194:197], v143 offset:36864
	ds_read_b128 v[198:201], v143 offset:37888
	ds_read_b128 v[202:205], v143 offset:38912
	ds_read_b128 v[206:209], v143 offset:39936
	s_waitcnt vmcnt(8)
	s_waitcnt lgkmcnt(0)
	s_barrier
	s_waitcnt lgkmcnt(0)
	v_mfma_f32_16x16x32_bf16 v[124:127], v[146:149], v[178:181], v[124:127]
	v_mfma_f32_16x16x32_bf16 v[108:111], v[146:149], v[186:189], v[108:111]
	v_mfma_f32_16x16x32_bf16 v[92:95], v[146:149], v[194:197], v[92:95]
	v_mfma_f32_16x16x32_bf16 v[76:79], v[146:149], v[202:205], v[76:79]
	v_mfma_f32_16x16x32_bf16 v[64:67], v[154:157], v[202:205], v[64:67]
	v_mfma_f32_16x16x32_bf16 v[80:83], v[154:157], v[194:197], v[80:83]
	v_mfma_f32_16x16x32_bf16 v[96:99], v[154:157], v[186:189], v[96:99]
	v_mfma_f32_16x16x32_bf16 v[112:115], v[154:157], v[178:181], v[112:115]
	v_mfma_f32_16x16x32_bf16 v[120:123], v[162:165], v[178:181], v[120:123]
	v_mfma_f32_16x16x32_bf16 v[104:107], v[162:165], v[186:189], v[104:107]
	v_mfma_f32_16x16x32_bf16 v[88:91], v[162:165], v[194:197], v[88:91]
	v_mfma_f32_16x16x32_bf16 v[72:75], v[162:165], v[202:205], v[72:75]
	v_mfma_f32_16x16x32_bf16 v[68:71], v[170:173], v[202:205], v[68:71]
	v_mfma_f32_16x16x32_bf16 v[84:87], v[170:173], v[194:197], v[84:87]
	v_mfma_f32_16x16x32_bf16 v[100:103], v[170:173], v[186:189], v[100:103]
	v_mfma_f32_16x16x32_bf16 v[116:119], v[170:173], v[178:181], v[116:119]
	v_mfma_f32_16x16x32_bf16 v[124:127], v[150:153], v[182:185], v[124:127]
	v_mfma_f32_16x16x32_bf16 v[108:111], v[150:153], v[190:193], v[108:111]
	v_mfma_f32_16x16x32_bf16 v[92:95], v[150:153], v[198:201], v[92:95]
	v_mfma_f32_16x16x32_bf16 v[76:79], v[150:153], v[206:209], v[76:79]
	v_mfma_f32_16x16x32_bf16 v[64:67], v[158:161], v[206:209], v[64:67]
	v_mfma_f32_16x16x32_bf16 v[80:83], v[158:161], v[198:201], v[80:83]
	v_mfma_f32_16x16x32_bf16 v[96:99], v[158:161], v[190:193], v[96:99]
	v_mfma_f32_16x16x32_bf16 v[112:115], v[158:161], v[182:185], v[112:115]
	v_mfma_f32_16x16x32_bf16 v[120:123], v[166:169], v[182:185], v[120:123]
	v_mfma_f32_16x16x32_bf16 v[104:107], v[166:169], v[190:193], v[104:107]
	v_mfma_f32_16x16x32_bf16 v[88:91], v[166:169], v[198:201], v[88:91]
	v_mfma_f32_16x16x32_bf16 v[72:75], v[166:169], v[206:209], v[72:75]
	v_mfma_f32_16x16x32_bf16 v[68:71], v[174:177], v[206:209], v[68:71]
	v_mfma_f32_16x16x32_bf16 v[84:87], v[174:177], v[198:201], v[84:87]
	v_mfma_f32_16x16x32_bf16 v[100:103], v[174:177], v[190:193], v[100:103]
	v_mfma_f32_16x16x32_bf16 v[116:119], v[174:177], v[182:185], v[116:119]
	s_barrier
	s_mov_b32 m0, s77
	v_lshl_add_u64 v[216:217], v[212:213], 0, s[18:19]
	global_load_lds_dwordx4 v[216:217], off
	v_lshl_add_u64 v[216:217], v[212:213], 0, s[20:21]
	s_mov_b32 m0, s78
	s_nop 0
	global_load_lds_dwordx4 v[216:217], off
	v_lshl_add_u64 v[216:217], v[212:213], 0, s[22:23]
	s_mov_b32 m0, s79
	v_lshl_add_u64 v[212:213], v[212:213], 0, s[24:25]
	global_load_lds_dwordx4 v[216:217], off
	s_mov_b32 m0, s80
	s_nop 0
	global_load_lds_dwordx4 v[212:213], off
	v_lshl_add_u64 v[212:213], v[214:215], 0, s[18:19]
	s_mov_b32 m0, s60
	s_nop 0
	global_load_lds_dwordx4 v[212:213], off
	v_lshl_add_u64 v[212:213], v[214:215], 0, s[20:21]
	s_mov_b32 m0, s61
	s_nop 0
	global_load_lds_dwordx4 v[212:213], off
	ds_read_b128 v[178:181], v143 offset:49152
	ds_read_b128 v[182:185], v143 offset:50176
	ds_read_b128 v[186:189], v143 offset:51200
	ds_read_b128 v[190:193], v143 offset:52224
	ds_read_b128 v[194:197], v143 offset:53248
	ds_read_b128 v[198:201], v143 offset:54272
	ds_read_b128 v[202:205], v143 offset:55296
	ds_read_b128 v[206:209], v143 offset:56320
	s_waitcnt vmcnt(8)
	s_waitcnt lgkmcnt(0)
	s_barrier
	s_waitcnt lgkmcnt(0)
	v_mfma_f32_16x16x32_bf16 v[60:63], v[146:149], v[178:181], v[60:63]
	v_mfma_f32_16x16x32_bf16 v[44:47], v[146:149], v[186:189], v[44:47]
	v_mfma_f32_16x16x32_bf16 v[28:31], v[146:149], v[194:197], v[28:31]
	v_mfma_f32_16x16x32_bf16 v[12:15], v[146:149], v[202:205], v[12:15]
	v_mfma_f32_16x16x32_bf16 v[0:3], v[154:157], v[202:205], v[0:3]
	v_mfma_f32_16x16x32_bf16 v[16:19], v[154:157], v[194:197], v[16:19]
	v_mfma_f32_16x16x32_bf16 v[32:35], v[154:157], v[186:189], v[32:35]
	v_mfma_f32_16x16x32_bf16 v[48:51], v[154:157], v[178:181], v[48:51]
	v_mfma_f32_16x16x32_bf16 v[56:59], v[162:165], v[178:181], v[56:59]
	v_mfma_f32_16x16x32_bf16 v[40:43], v[162:165], v[186:189], v[40:43]
	v_mfma_f32_16x16x32_bf16 v[24:27], v[162:165], v[194:197], v[24:27]
	v_mfma_f32_16x16x32_bf16 v[8:11], v[162:165], v[202:205], v[8:11]
	v_mfma_f32_16x16x32_bf16 v[4:7], v[170:173], v[202:205], v[4:7]
	v_mfma_f32_16x16x32_bf16 v[20:23], v[170:173], v[194:197], v[20:23]
	v_mfma_f32_16x16x32_bf16 v[36:39], v[170:173], v[186:189], v[36:39]
	v_mfma_f32_16x16x32_bf16 v[52:55], v[170:173], v[178:181], v[52:55]
	v_mfma_f32_16x16x32_bf16 v[60:63], v[150:153], v[182:185], v[60:63]
	v_mfma_f32_16x16x32_bf16 v[44:47], v[150:153], v[190:193], v[44:47]
	v_mfma_f32_16x16x32_bf16 v[28:31], v[150:153], v[198:201], v[28:31]
	v_mfma_f32_16x16x32_bf16 v[12:15], v[150:153], v[206:209], v[12:15]
	v_mfma_f32_16x16x32_bf16 v[0:3], v[158:161], v[206:209], v[0:3]
	v_mfma_f32_16x16x32_bf16 v[16:19], v[158:161], v[198:201], v[16:19]
	v_mfma_f32_16x16x32_bf16 v[32:35], v[158:161], v[190:193], v[32:35]
	v_mfma_f32_16x16x32_bf16 v[48:51], v[158:161], v[182:185], v[48:51]
	v_mfma_f32_16x16x32_bf16 v[56:59], v[166:169], v[182:185], v[56:59]
	v_mfma_f32_16x16x32_bf16 v[40:43], v[166:169], v[190:193], v[40:43]
	v_mfma_f32_16x16x32_bf16 v[24:27], v[166:169], v[198:201], v[24:27]
	v_mfma_f32_16x16x32_bf16 v[8:11], v[166:169], v[206:209], v[8:11]
	v_mfma_f32_16x16x32_bf16 v[4:7], v[174:177], v[206:209], v[4:7]
	v_mfma_f32_16x16x32_bf16 v[20:23], v[174:177], v[198:201], v[20:23]
	v_mfma_f32_16x16x32_bf16 v[36:39], v[174:177], v[190:193], v[36:39]
	v_mfma_f32_16x16x32_bf16 v[52:55], v[174:177], v[182:185], v[52:55]
	s_barrier
	s_cmp_gt_u32 s29, 13
	s_cbranch_scc0 .LBB0_175
	s_and_b64 vcc, exec, s[26:27]
	s_cbranch_vccz .LBB0_178
	s_barrier

.LBB0_255:
	s_add_i32 s73, s73, 2
	s_mov_b32 s74, s73
	s_ashr_i32 s75, s74, 31
	s_lshl_b64 s[76:77], s[74:75], 7
	s_add_u32 s75, s76, 0x100
	s_addc_u32 s78, s77, 0
	s_add_u32 s79, s40, s75
	s_addc_u32 s80, s41, s78
	s_add_u32 s81, s38, s75
	s_addc_u32 s78, s39, s78
	s_cmp_eq_u32 s74, 42
	s_cselect_b32 s75, s1, s80
	s_cselect_b32 s74, s0, s79
	s_cselect_b32 s79, s43, s78
	s_cselect_b32 s78, s42, s81
	v_lshl_add_u64 v[208:209], v[136:137], 0, s[76:77]
	v_lshl_add_u64 v[212:213], v[208:209], 0, s[20:21]
	s_add_i32 m0, s53, 0xc000
	s_nop 0
	global_load_lds_dwordx4 v[212:213], off
	v_lshl_add_u64 v[208:209], v[208:209], 0, s[22:23]
	s_add_i32 m0, s53, 0xe000
	s_nop 0
	global_load_lds_dwordx4 v[208:209], off
	ds_read_b128 v[144:147], v141
	ds_read_b128 v[148:151], v141 offset:1024
	ds_read_b128 v[152:155], v141 offset:2048
	ds_read_b128 v[156:159], v141 offset:3072
	ds_read_b128 v[160:163], v142
	ds_read_b128 v[164:167], v142 offset:1024
	ds_read_b128 v[168:171], v142 offset:2048
	ds_read_b128 v[172:175], v142 offset:3072
	ds_read_b128 v[176:179], v143
	ds_read_b128 v[180:183], v143 offset:1024
	ds_read_b128 v[184:187], v143 offset:2048
	ds_read_b128 v[188:191], v143 offset:3072
	ds_read_b128 v[192:195], v143 offset:4096
	ds_read_b128 v[196:199], v143 offset:5120
	ds_read_b128 v[200:203], v143 offset:6144
	ds_read_b128 v[204:207], v143 offset:7168
	s_waitcnt vmcnt(8)
	s_waitcnt lgkmcnt(0)
	s_barrier
	s_waitcnt lgkmcnt(0)
	v_mfma_f32_16x16x32_bf16 v[124:127], v[144:147], v[176:179], v[124:127]
	v_mfma_f32_16x16x32_bf16 v[116:119], v[144:147], v[184:187], v[116:119]
	v_mfma_f32_16x16x32_bf16 v[100:103], v[144:147], v[192:195], v[100:103]
	v_mfma_f32_16x16x32_bf16 v[84:87], v[144:147], v[200:203], v[84:87]
	v_mfma_f32_16x16x32_bf16 v[80:83], v[152:155], v[200:203], v[80:83]
	v_mfma_f32_16x16x32_bf16 v[96:99], v[152:155], v[192:195], v[96:99]
	v_mfma_f32_16x16x32_bf16 v[112:115], v[152:155], v[184:187], v[112:115]
	v_mfma_f32_16x16x32_bf16 v[120:123], v[152:155], v[176:179], v[120:123]
	v_mfma_f32_16x16x32_bf16 v[108:111], v[160:163], v[176:179], v[108:111]
	v_mfma_f32_16x16x32_bf16 v[92:95], v[160:163], v[184:187], v[92:95]
	v_mfma_f32_16x16x32_bf16 v[76:79], v[160:163], v[192:195], v[76:79]
	v_mfma_f32_16x16x32_bf16 v[68:71], v[160:163], v[200:203], v[68:71]
	v_mfma_f32_16x16x32_bf16 v[64:67], v[168:171], v[200:203], v[64:67]
	v_mfma_f32_16x16x32_bf16 v[72:75], v[168:171], v[192:195], v[72:75]
	v_mfma_f32_16x16x32_bf16 v[88:91], v[168:171], v[184:187], v[88:91]
	v_mfma_f32_16x16x32_bf16 v[104:107], v[168:171], v[176:179], v[104:107]
	v_mfma_f32_16x16x32_bf16 v[124:127], v[148:151], v[180:183], v[124:127]
	v_mfma_f32_16x16x32_bf16 v[116:119], v[148:151], v[188:191], v[116:119]
	v_mfma_f32_16x16x32_bf16 v[100:103], v[148:151], v[196:199], v[100:103]
	v_mfma_f32_16x16x32_bf16 v[84:87], v[148:151], v[204:207], v[84:87]
	v_mfma_f32_16x16x32_bf16 v[80:83], v[156:159], v[204:207], v[80:83]
	v_mfma_f32_16x16x32_bf16 v[96:99], v[156:159], v[196:199], v[96:99]
	v_mfma_f32_16x16x32_bf16 v[112:115], v[156:159], v[188:191], v[112:115]
	v_mfma_f32_16x16x32_bf16 v[120:123], v[156:159], v[180:183], v[120:123]
	v_mfma_f32_16x16x32_bf16 v[108:111], v[164:167], v[180:183], v[108:111]
	v_mfma_f32_16x16x32_bf16 v[92:95], v[164:167], v[188:191], v[92:95]
	v_mfma_f32_16x16x32_bf16 v[76:79], v[164:167], v[196:199], v[76:79]
	v_mfma_f32_16x16x32_bf16 v[68:71], v[164:167], v[204:207], v[68:71]
	v_mfma_f32_16x16x32_bf16 v[64:67], v[172:175], v[204:207], v[64:67]
	v_mfma_f32_16x16x32_bf16 v[72:75], v[172:175], v[196:199], v[72:75]
	v_mfma_f32_16x16x32_bf16 v[88:91], v[172:175], v[188:191], v[88:91]
	v_mfma_f32_16x16x32_bf16 v[104:107], v[172:175], v[180:183], v[104:107]
	s_barrier
	s_add_i32 s76, s63, s52
	v_lshl_add_u64 v[208:209], s[78:79], 0, v[130:131]
	s_mov_b32 m0, s76
	s_nop 0
	global_load_lds_dwordx4 v[208:209], off
	v_lshl_add_u64 v[212:213], v[208:209], 0, s[2:3]
	s_add_i32 m0, s76, 0x2000
	s_add_i32 s76, s64, s52
	global_load_lds_dwordx4 v[212:213], off
	v_lshl_add_u64 v[212:213], v[208:209], 0, s[8:9]
	s_mov_b32 m0, s76
	s_nop 0
	global_load_lds_dwordx4 v[212:213], off
	v_lshl_add_u64 v[212:213], v[208:209], 0, s[14:15]
	s_add_i32 m0, s76, 0x2000
	s_nop 0
	global_load_lds_dwordx4 v[212:213], off
	v_lshl_add_u64 v[212:213], s[74:75], 0, v[128:129]
	s_mov_b32 m0, s53
	v_lshl_add_u64 v[214:215], v[212:213], 0, s[2:3]
	global_load_lds_dwordx4 v[212:213], off
	s_mov_b32 m0, s54
	s_nop 0
	global_load_lds_dwordx4 v[214:215], off
	ds_read_b128 v[176:179], v143 offset:16384
	ds_read_b128 v[180:183], v143 offset:17408
	ds_read_b128 v[184:187], v143 offset:18432
	ds_read_b128 v[188:191], v143 offset:19456
	ds_read_b128 v[192:195], v143 offset:20480
	ds_read_b128 v[196:199], v143 offset:21504
	ds_read_b128 v[200:203], v143 offset:22528
	ds_read_b128 v[204:207], v143 offset:23552
	s_waitcnt vmcnt(8)
	s_waitcnt lgkmcnt(0)
	s_barrier
	s_waitcnt lgkmcnt(0)
	v_mfma_f32_16x16x32_bf16 v[60:63], v[144:147], v[176:179], v[60:63]
	v_mfma_f32_16x16x32_bf16 v[52:55], v[144:147], v[184:187], v[52:55]
	v_mfma_f32_16x16x32_bf16 v[36:39], v[144:147], v[192:195], v[36:39]
	v_mfma_f32_16x16x32_bf16 v[20:23], v[144:147], v[200:203], v[20:23]
	v_mfma_f32_16x16x32_bf16 v[16:19], v[152:155], v[200:203], v[16:19]
	v_mfma_f32_16x16x32_bf16 v[32:35], v[152:155], v[192:195], v[32:35]
	v_mfma_f32_16x16x32_bf16 v[48:51], v[152:155], v[184:187], v[48:51]
	v_mfma_f32_16x16x32_bf16 v[56:59], v[152:155], v[176:179], v[56:59]
	v_mfma_f32_16x16x32_bf16 v[44:47], v[160:163], v[176:179], v[44:47]
	v_mfma_f32_16x16x32_bf16 v[28:31], v[160:163], v[184:187], v[28:31]
	v_mfma_f32_16x16x32_bf16 v[12:15], v[160:163], v[192:195], v[12:15]
	v_mfma_f32_16x16x32_bf16 v[4:7], v[160:163], v[200:203], v[4:7]
	v_mfma_f32_16x16x32_bf16 v[0:3], v[168:171], v[200:203], v[0:3]
	v_mfma_f32_16x16x32_bf16 v[8:11], v[168:171], v[192:195], v[8:11]
	v_mfma_f32_16x16x32_bf16 v[24:27], v[168:171], v[184:187], v[24:27]
	v_mfma_f32_16x16x32_bf16 v[40:43], v[168:171], v[176:179], v[40:43]
	v_mfma_f32_16x16x32_bf16 v[60:63], v[148:151], v[180:183], v[60:63]
	v_mfma_f32_16x16x32_bf16 v[52:55], v[148:151], v[188:191], v[52:55]
	v_mfma_f32_16x16x32_bf16 v[36:39], v[148:151], v[196:199], v[36:39]
	v_mfma_f32_16x16x32_bf16 v[20:23], v[148:151], v[204:207], v[20:23]
	v_mfma_f32_16x16x32_bf16 v[16:19], v[156:159], v[204:207], v[16:19]
	v_mfma_f32_16x16x32_bf16 v[32:35], v[156:159], v[196:199], v[32:35]
	v_mfma_f32_16x16x32_bf16 v[48:51], v[156:159], v[188:191], v[48:51]
	v_mfma_f32_16x16x32_bf16 v[56:59], v[156:159], v[180:183], v[56:59]
	v_mfma_f32_16x16x32_bf16 v[44:47], v[164:167], v[180:183], v[44:47]
	v_mfma_f32_16x16x32_bf16 v[28:31], v[164:167], v[188:191], v[28:31]
	v_mfma_f32_16x16x32_bf16 v[12:15], v[164:167], v[196:199], v[12:15]
	v_mfma_f32_16x16x32_bf16 v[4:7], v[164:167], v[204:207], v[4:7]
	v_mfma_f32_16x16x32_bf16 v[0:3], v[172:175], v[204:207], v[0:3]
	v_mfma_f32_16x16x32_bf16 v[8:11], v[172:175], v[196:199], v[8:11]
	v_mfma_f32_16x16x32_bf16 v[24:27], v[172:175], v[188:191], v[24:27]
	v_mfma_f32_16x16x32_bf16 v[40:43], v[172:175], v[180:183], v[40:43]
	s_barrier
	s_add_i32 s74, 0, 0x18000
	s_add_i32 s75, 0, 0x1c000
	v_add_u32_e32 v156, s74, v140
	v_add_u32_e32 v172, s75, v140
	s_mov_b32 m0, s55
	v_lshl_add_u64 v[214:215], v[212:213], 0, s[8:9]
	global_load_lds_dwordx4 v[214:215], off
	v_lshl_add_u64 v[214:215], v[212:213], 0, s[14:15]
	s_mov_b32 m0, s56
	s_nop 0
	global_load_lds_dwordx4 v[214:215], off
	ds_read_b128 v[144:147], v156
	ds_read_b128 v[148:151], v156 offset:1024
	ds_read_b128 v[152:155], v156 offset:2048
	ds_read_b128 v[156:159], v156 offset:3072
	ds_read_b128 v[160:163], v172
	ds_read_b128 v[164:167], v172 offset:1024
	ds_read_b128 v[168:171], v172 offset:2048
	ds_read_b128 v[172:175], v172 offset:3072
	ds_read_b128 v[176:179], v143 offset:32768
	ds_read_b128 v[180:183], v143 offset:33792
	ds_read_b128 v[184:187], v143 offset:34816
	ds_read_b128 v[188:191], v143 offset:35840
	ds_read_b128 v[192:195], v143 offset:36864
	ds_read_b128 v[196:199], v143 offset:37888
	ds_read_b128 v[200:203], v143 offset:38912
	ds_read_b128 v[204:207], v143 offset:39936
	s_waitcnt vmcnt(8)
	s_waitcnt lgkmcnt(0)
	s_barrier
	s_waitcnt lgkmcnt(0)
	v_mfma_f32_16x16x32_bf16 v[124:127], v[144:147], v[176:179], v[124:127]
	v_mfma_f32_16x16x32_bf16 v[116:119], v[144:147], v[184:187], v[116:119]
	v_mfma_f32_16x16x32_bf16 v[100:103], v[144:147], v[192:195], v[100:103]
	v_mfma_f32_16x16x32_bf16 v[84:87], v[144:147], v[200:203], v[84:87]
	v_mfma_f32_16x16x32_bf16 v[80:83], v[152:155], v[200:203], v[80:83]
	v_mfma_f32_16x16x32_bf16 v[96:99], v[152:155], v[192:195], v[96:99]
	v_mfma_f32_16x16x32_bf16 v[112:115], v[152:155], v[184:187], v[112:115]
	v_mfma_f32_16x16x32_bf16 v[120:123], v[152:155], v[176:179], v[120:123]
	v_mfma_f32_16x16x32_bf16 v[108:111], v[160:163], v[176:179], v[108:111]
	v_mfma_f32_16x16x32_bf16 v[92:95], v[160:163], v[184:187], v[92:95]
	v_mfma_f32_16x16x32_bf16 v[76:79], v[160:163], v[192:195], v[76:79]
	v_mfma_f32_16x16x32_bf16 v[68:71], v[160:163], v[200:203], v[68:71]
	v_mfma_f32_16x16x32_bf16 v[64:67], v[168:171], v[200:203], v[64:67]
	v_mfma_f32_16x16x32_bf16 v[72:75], v[168:171], v[192:195], v[72:75]
	v_mfma_f32_16x16x32_bf16 v[88:91], v[168:171], v[184:187], v[88:91]
	v_mfma_f32_16x16x32_bf16 v[104:107], v[168:171], v[176:179], v[104:107]
	v_mfma_f32_16x16x32_bf16 v[124:127], v[148:151], v[180:183], v[124:127]
	v_mfma_f32_16x16x32_bf16 v[116:119], v[148:151], v[188:191], v[116:119]
	v_mfma_f32_16x16x32_bf16 v[100:103], v[148:151], v[196:199], v[100:103]
	v_mfma_f32_16x16x32_bf16 v[84:87], v[148:151], v[204:207], v[84:87]
	v_mfma_f32_16x16x32_bf16 v[80:83], v[156:159], v[204:207], v[80:83]
	v_mfma_f32_16x16x32_bf16 v[96:99], v[156:159], v[196:199], v[96:99]
	v_mfma_f32_16x16x32_bf16 v[112:115], v[156:159], v[188:191], v[112:115]
	v_mfma_f32_16x16x32_bf16 v[120:123], v[156:159], v[180:183], v[120:123]
	v_mfma_f32_16x16x32_bf16 v[108:111], v[164:167], v[180:183], v[108:111]
	v_mfma_f32_16x16x32_bf16 v[92:95], v[164:167], v[188:191], v[92:95]
	v_mfma_f32_16x16x32_bf16 v[76:79], v[164:167], v[196:199], v[76:79]
	v_mfma_f32_16x16x32_bf16 v[68:71], v[164:167], v[204:207], v[68:71]
	v_mfma_f32_16x16x32_bf16 v[64:67], v[172:175], v[204:207], v[64:67]
	v_mfma_f32_16x16x32_bf16 v[72:75], v[172:175], v[196:199], v[72:75]
	v_mfma_f32_16x16x32_bf16 v[88:91], v[172:175], v[188:191], v[88:91]
	v_mfma_f32_16x16x32_bf16 v[104:107], v[172:175], v[180:183], v[104:107]
	s_barrier
	s_add_i32 s74, s74, s52
	v_lshl_add_u64 v[214:215], v[208:209], 0, s[20:21]
	s_mov_b32 m0, s74
	s_nop 0
	global_load_lds_dwordx4 v[214:215], off
	v_lshl_add_u64 v[214:215], v[208:209], 0, s[22:23]
	s_add_i32 m0, s74, 0x2000
	s_add_i32 s74, s75, s52
	global_load_lds_dwordx4 v[214:215], off
	v_lshl_add_u64 v[214:215], v[208:209], 0, s[24:25]
	s_mov_b32 m0, s74
	v_lshl_add_u64 v[208:209], v[208:209], 0, s[26:27]
	global_load_lds_dwordx4 v[214:215], off
	s_add_i32 m0, s74, 0x2000
	s_nop 0
	global_load_lds_dwordx4 v[208:209], off
	v_lshl_add_u64 v[208:209], v[212:213], 0, s[20:21]
	s_mov_b32 m0, s58
	s_nop 0
	global_load_lds_dwordx4 v[208:209], off
	v_lshl_add_u64 v[208:209], v[212:213], 0, s[22:23]
	s_mov_b32 m0, s59
	s_nop 0
	global_load_lds_dwordx4 v[208:209], off
	ds_read_b128 v[176:179], v143 offset:49152
	ds_read_b128 v[180:183], v143 offset:50176
	ds_read_b128 v[184:187], v143 offset:51200
	ds_read_b128 v[188:191], v143 offset:52224
	ds_read_b128 v[192:195], v143 offset:53248
	ds_read_b128 v[196:199], v143 offset:54272
	ds_read_b128 v[200:203], v143 offset:55296
	ds_read_b128 v[204:207], v143 offset:56320
	s_waitcnt vmcnt(8)
	s_waitcnt lgkmcnt(0)
	s_barrier
	s_waitcnt lgkmcnt(0)
	v_mfma_f32_16x16x32_bf16 v[60:63], v[144:147], v[176:179], v[60:63]
	v_mfma_f32_16x16x32_bf16 v[52:55], v[144:147], v[184:187], v[52:55]
	v_mfma_f32_16x16x32_bf16 v[36:39], v[144:147], v[192:195], v[36:39]
	v_mfma_f32_16x16x32_bf16 v[20:23], v[144:147], v[200:203], v[20:23]
	v_mfma_f32_16x16x32_bf16 v[16:19], v[152:155], v[200:203], v[16:19]
	v_mfma_f32_16x16x32_bf16 v[32:35], v[152:155], v[192:195], v[32:35]
	v_mfma_f32_16x16x32_bf16 v[48:51], v[152:155], v[184:187], v[48:51]
	v_mfma_f32_16x16x32_bf16 v[56:59], v[152:155], v[176:179], v[56:59]
	v_mfma_f32_16x16x32_bf16 v[44:47], v[160:163], v[176:179], v[44:47]
	v_mfma_f32_16x16x32_bf16 v[28:31], v[160:163], v[184:187], v[28:31]
	v_mfma_f32_16x16x32_bf16 v[12:15], v[160:163], v[192:195], v[12:15]
	v_mfma_f32_16x16x32_bf16 v[4:7], v[160:163], v[200:203], v[4:7]
	v_mfma_f32_16x16x32_bf16 v[0:3], v[168:171], v[200:203], v[0:3]
	v_mfma_f32_16x16x32_bf16 v[8:11], v[168:171], v[192:195], v[8:11]
	v_mfma_f32_16x16x32_bf16 v[24:27], v[168:171], v[184:187], v[24:27]
	v_mfma_f32_16x16x32_bf16 v[40:43], v[168:171], v[176:179], v[40:43]
	v_mfma_f32_16x16x32_bf16 v[60:63], v[148:151], v[180:183], v[60:63]
	v_mfma_f32_16x16x32_bf16 v[52:55], v[148:151], v[188:191], v[52:55]
	v_mfma_f32_16x16x32_bf16 v[36:39], v[148:151], v[196:199], v[36:39]
	v_mfma_f32_16x16x32_bf16 v[20:23], v[148:151], v[204:207], v[20:23]
	v_mfma_f32_16x16x32_bf16 v[16:19], v[156:159], v[204:207], v[16:19]
	v_mfma_f32_16x16x32_bf16 v[32:35], v[156:159], v[196:199], v[32:35]
	v_mfma_f32_16x16x32_bf16 v[48:51], v[156:159], v[188:191], v[48:51]
	v_mfma_f32_16x16x32_bf16 v[56:59], v[156:159], v[180:183], v[56:59]
	v_mfma_f32_16x16x32_bf16 v[44:47], v[164:167], v[180:183], v[44:47]
	v_mfma_f32_16x16x32_bf16 v[28:31], v[164:167], v[188:191], v[28:31]
	v_mfma_f32_16x16x32_bf16 v[12:15], v[164:167], v[196:199], v[12:15]
	v_mfma_f32_16x16x32_bf16 v[4:7], v[164:167], v[204:207], v[4:7]
	v_mfma_f32_16x16x32_bf16 v[0:3], v[172:175], v[204:207], v[0:3]
	v_mfma_f32_16x16x32_bf16 v[8:11], v[172:175], v[196:199], v[8:11]
	v_mfma_f32_16x16x32_bf16 v[24:27], v[172:175], v[188:191], v[24:27]
	v_mfma_f32_16x16x32_bf16 v[40:43], v[172:175], v[180:183], v[40:43]
	s_barrier
	s_cmp_gt_u32 s73, 41
	s_cbranch_scc0 .LBB0_255
	s_and_b64 vcc, exec, s[28:29]
	s_cbranch_vccz .LBB0_258
	s_barrier

.LBB0_386:
	s_add_i32 s70, s70, 2
	s_mov_b32 s42, s70
	s_ashr_i32 s43, s42, 31
	s_lshl_b64 s[72:73], s[42:43], 7
	s_add_u32 s43, s72, 0x100
	s_addc_u32 s71, s73, 0
	s_add_u32 s79, s8, s43
	s_addc_u32 s80, s9, s71
	s_add_u32 s82, s2, s43
	s_addc_u32 s71, s3, s71
	s_add_i32 s83, 0, 0x10000
	s_cmp_eq_u32 s42, 14
	s_cselect_b32 s43, s1, s80
	s_cselect_b32 s42, s57, s79
	s_cselect_b32 s81, s68, s71
	s_cselect_b32 s80, s69, s82
	s_add_i32 s71, 0, 0x14000
	v_add_u32_e32 v140, s83, v220
	v_add_u32_e32 v156, s71, v220
	s_add_u32 s72, s8, s72
	s_addc_u32 s73, s9, s73
	v_lshl_add_u64 v[222:223], s[72:73], 0, v[182:183]
	v_lshl_add_u64 v[224:225], v[222:223], 0, s[14:15]
	s_add_i32 m0, s39, 0xc000
	s_nop 0
	global_load_lds_dwordx4 v[224:225], off
	v_lshl_add_u64 v[222:223], v[222:223], 0, s[16:17]
	s_add_i32 m0, s39, 0xe000
	s_nop 0
	global_load_lds_dwordx4 v[222:223], off
	ds_read_b128 v[128:131], v140
	ds_read_b128 v[132:135], v140 offset:1024
	ds_read_b128 v[136:139], v140 offset:2048
	ds_read_b128 v[140:143], v140 offset:3072
	ds_read_b128 v[144:147], v156
	ds_read_b128 v[148:151], v156 offset:1024
	ds_read_b128 v[152:155], v156 offset:2048
	ds_read_b128 v[156:159], v156 offset:3072
	ds_read_b128 v[160:163], v221
	ds_read_b128 v[164:167], v221 offset:1024
	ds_read_b128 v[186:189], v221 offset:2048
	ds_read_b128 v[190:193], v221 offset:3072
	ds_read_b128 v[194:197], v221 offset:4096
	ds_read_b128 v[198:201], v221 offset:5120
	ds_read_b128 v[202:205], v221 offset:6144
	ds_read_b128 v[206:209], v221 offset:7168
	s_waitcnt vmcnt(8)
	s_waitcnt lgkmcnt(0)
	s_barrier
	s_waitcnt lgkmcnt(0)
	v_mfma_f32_16x16x32_bf16 v[124:127], v[128:131], v[160:163], v[124:127]
	v_mfma_f32_16x16x32_bf16 v[112:115], v[128:131], v[186:189], v[112:115]
	v_mfma_f32_16x16x32_bf16 v[96:99], v[128:131], v[194:197], v[96:99]
	v_mfma_f32_16x16x32_bf16 v[80:83], v[128:131], v[202:205], v[80:83]
	v_mfma_f32_16x16x32_bf16 v[72:75], v[136:139], v[202:205], v[72:75]
	v_mfma_f32_16x16x32_bf16 v[88:91], v[136:139], v[194:197], v[88:91]
	v_mfma_f32_16x16x32_bf16 v[104:107], v[136:139], v[186:189], v[104:107]
	v_mfma_f32_16x16x32_bf16 v[120:123], v[136:139], v[160:163], v[120:123]
	v_mfma_f32_16x16x32_bf16 v[116:119], v[144:147], v[160:163], v[116:119]
	v_mfma_f32_16x16x32_bf16 v[100:103], v[144:147], v[186:189], v[100:103]
	v_mfma_f32_16x16x32_bf16 v[84:87], v[144:147], v[194:197], v[84:87]
	v_mfma_f32_16x16x32_bf16 v[68:71], v[144:147], v[202:205], v[68:71]
	v_mfma_f32_16x16x32_bf16 v[64:67], v[152:155], v[202:205], v[64:67]
	v_mfma_f32_16x16x32_bf16 v[76:79], v[152:155], v[194:197], v[76:79]
	v_mfma_f32_16x16x32_bf16 v[92:95], v[152:155], v[186:189], v[92:95]
	v_mfma_f32_16x16x32_bf16 v[108:111], v[152:155], v[160:163], v[108:111]
	v_mfma_f32_16x16x32_bf16 v[124:127], v[132:135], v[164:167], v[124:127]
	v_mfma_f32_16x16x32_bf16 v[112:115], v[132:135], v[190:193], v[112:115]
	v_mfma_f32_16x16x32_bf16 v[96:99], v[132:135], v[198:201], v[96:99]
	v_mfma_f32_16x16x32_bf16 v[80:83], v[132:135], v[206:209], v[80:83]
	v_mfma_f32_16x16x32_bf16 v[72:75], v[140:143], v[206:209], v[72:75]
	v_mfma_f32_16x16x32_bf16 v[88:91], v[140:143], v[198:201], v[88:91]
	v_mfma_f32_16x16x32_bf16 v[104:107], v[140:143], v[190:193], v[104:107]
	v_mfma_f32_16x16x32_bf16 v[120:123], v[140:143], v[164:167], v[120:123]
	v_mfma_f32_16x16x32_bf16 v[116:119], v[148:151], v[164:167], v[116:119]
	v_mfma_f32_16x16x32_bf16 v[100:103], v[148:151], v[190:193], v[100:103]
	v_mfma_f32_16x16x32_bf16 v[84:87], v[148:151], v[198:201], v[84:87]
	v_mfma_f32_16x16x32_bf16 v[68:71], v[148:151], v[206:209], v[68:71]
	v_mfma_f32_16x16x32_bf16 v[64:67], v[156:159], v[206:209], v[64:67]
	v_mfma_f32_16x16x32_bf16 v[76:79], v[156:159], v[198:201], v[76:79]
	v_mfma_f32_16x16x32_bf16 v[92:95], v[156:159], v[190:193], v[92:95]
	v_mfma_f32_16x16x32_bf16 v[108:111], v[156:159], v[164:167], v[108:111]
	s_barrier
	s_add_i32 s72, s83, s74
	v_lshl_add_u64 v[222:223], s[80:81], 0, v[184:185]
	s_mov_b32 m0, s72
	s_nop 0
	global_load_lds_dwordx4 v[222:223], off
	v_lshl_add_u64 v[224:225], v[222:223], 0, s[40:41]
	s_add_i32 m0, s72, 0x2000
	s_add_i32 s71, s71, s74
	global_load_lds_dwordx4 v[224:225], off
	v_lshl_add_u64 v[224:225], v[222:223], 0, s[4:5]
	s_mov_b32 m0, s71
	s_nop 0
	global_load_lds_dwordx4 v[224:225], off
	v_lshl_add_u64 v[224:225], v[222:223], 0, s[6:7]
	s_add_i32 m0, s71, 0x2000
	s_nop 0
	global_load_lds_dwordx4 v[224:225], off
	v_lshl_add_u64 v[224:225], s[42:43], 0, v[182:183]
	s_mov_b32 m0, s39
	v_lshl_add_u64 v[226:227], v[224:225], 0, s[40:41]
	global_load_lds_dwordx4 v[224:225], off
	s_mov_b32 m0, s75
	s_nop 0
	global_load_lds_dwordx4 v[226:227], off
	ds_read_b128 v[160:163], v221 offset:16384
	ds_read_b128 v[164:167], v221 offset:17408
	ds_read_b128 v[186:189], v221 offset:18432
	ds_read_b128 v[190:193], v221 offset:19456
	ds_read_b128 v[194:197], v221 offset:20480
	ds_read_b128 v[198:201], v221 offset:21504
	ds_read_b128 v[202:205], v221 offset:22528
	ds_read_b128 v[206:209], v221 offset:23552
	s_waitcnt vmcnt(8)
	s_waitcnt lgkmcnt(0)
	s_barrier
	s_waitcnt lgkmcnt(0)
	v_mfma_f32_16x16x32_bf16 v[60:63], v[128:131], v[160:163], v[60:63]
	v_mfma_f32_16x16x32_bf16 v[48:51], v[128:131], v[186:189], v[48:51]
	v_mfma_f32_16x16x32_bf16 v[32:35], v[128:131], v[194:197], v[32:35]
	v_mfma_f32_16x16x32_bf16 v[16:19], v[128:131], v[202:205], v[16:19]
	v_mfma_f32_16x16x32_bf16 v[8:11], v[136:139], v[202:205], v[8:11]
	v_mfma_f32_16x16x32_bf16 v[24:27], v[136:139], v[194:197], v[24:27]
	v_mfma_f32_16x16x32_bf16 v[40:43], v[136:139], v[186:189], v[40:43]
	v_mfma_f32_16x16x32_bf16 v[56:59], v[136:139], v[160:163], v[56:59]
	v_mfma_f32_16x16x32_bf16 v[52:55], v[144:147], v[160:163], v[52:55]
	v_mfma_f32_16x16x32_bf16 v[36:39], v[144:147], v[186:189], v[36:39]
	v_mfma_f32_16x16x32_bf16 v[20:23], v[144:147], v[194:197], v[20:23]
	v_mfma_f32_16x16x32_bf16 v[4:7], v[144:147], v[202:205], v[4:7]
	v_mfma_f32_16x16x32_bf16 v[0:3], v[152:155], v[202:205], v[0:3]
	v_mfma_f32_16x16x32_bf16 v[12:15], v[152:155], v[194:197], v[12:15]
	v_mfma_f32_16x16x32_bf16 v[28:31], v[152:155], v[186:189], v[28:31]
	v_mfma_f32_16x16x32_bf16 v[44:47], v[152:155], v[160:163], v[44:47]
	v_mfma_f32_16x16x32_bf16 v[60:63], v[132:135], v[164:167], v[60:63]
	v_mfma_f32_16x16x32_bf16 v[48:51], v[132:135], v[190:193], v[48:51]
	v_mfma_f32_16x16x32_bf16 v[32:35], v[132:135], v[198:201], v[32:35]
	v_mfma_f32_16x16x32_bf16 v[16:19], v[132:135], v[206:209], v[16:19]
	v_mfma_f32_16x16x32_bf16 v[8:11], v[140:143], v[206:209], v[8:11]
	v_mfma_f32_16x16x32_bf16 v[24:27], v[140:143], v[198:201], v[24:27]
	v_mfma_f32_16x16x32_bf16 v[40:43], v[140:143], v[190:193], v[40:43]
	v_mfma_f32_16x16x32_bf16 v[56:59], v[140:143], v[164:167], v[56:59]
	v_mfma_f32_16x16x32_bf16 v[52:55], v[148:151], v[164:167], v[52:55]
	v_mfma_f32_16x16x32_bf16 v[36:39], v[148:151], v[190:193], v[36:39]
	v_mfma_f32_16x16x32_bf16 v[20:23], v[148:151], v[198:201], v[20:23]
	v_mfma_f32_16x16x32_bf16 v[4:7], v[148:151], v[206:209], v[4:7]
	v_mfma_f32_16x16x32_bf16 v[0:3], v[156:159], v[206:209], v[0:3]
	v_mfma_f32_16x16x32_bf16 v[12:15], v[156:159], v[198:201], v[12:15]
	v_mfma_f32_16x16x32_bf16 v[28:31], v[156:159], v[190:193], v[28:31]
	v_mfma_f32_16x16x32_bf16 v[44:47], v[156:159], v[164:167], v[44:47]
	s_barrier
	s_add_i32 s42, 0, 0x18000
	s_add_i32 s43, 0, 0x1c000
	v_add_u32_e32 v140, s42, v220
	v_add_u32_e32 v156, s43, v220
	s_mov_b32 m0, s30
	v_lshl_add_u64 v[226:227], v[224:225], 0, s[4:5]
	global_load_lds_dwordx4 v[226:227], off
	v_lshl_add_u64 v[226:227], v[224:225], 0, s[6:7]
	s_mov_b32 m0, s31
	s_nop 0
	global_load_lds_dwordx4 v[226:227], off
	ds_read_b128 v[128:131], v140
	ds_read_b128 v[132:135], v140 offset:1024
	ds_read_b128 v[136:139], v140 offset:2048
	ds_read_b128 v[140:143], v140 offset:3072
	ds_read_b128 v[144:147], v156
	ds_read_b128 v[148:151], v156 offset:1024
	ds_read_b128 v[152:155], v156 offset:2048
	ds_read_b128 v[156:159], v156 offset:3072
	ds_read_b128 v[160:163], v221 offset:32768
	ds_read_b128 v[164:167], v221 offset:33792
	ds_read_b128 v[186:189], v221 offset:34816
	ds_read_b128 v[190:193], v221 offset:35840
	ds_read_b128 v[194:197], v221 offset:36864
	ds_read_b128 v[198:201], v221 offset:37888
	ds_read_b128 v[202:205], v221 offset:38912
	ds_read_b128 v[206:209], v221 offset:39936
	s_waitcnt vmcnt(8)
	s_waitcnt lgkmcnt(0)
	s_barrier
	s_waitcnt lgkmcnt(0)
	v_mfma_f32_16x16x32_bf16 v[124:127], v[128:131], v[160:163], v[124:127]
	v_mfma_f32_16x16x32_bf16 v[112:115], v[128:131], v[186:189], v[112:115]
	v_mfma_f32_16x16x32_bf16 v[96:99], v[128:131], v[194:197], v[96:99]
	v_mfma_f32_16x16x32_bf16 v[80:83], v[128:131], v[202:205], v[80:83]
	v_mfma_f32_16x16x32_bf16 v[72:75], v[136:139], v[202:205], v[72:75]
	v_mfma_f32_16x16x32_bf16 v[88:91], v[136:139], v[194:197], v[88:91]
	v_mfma_f32_16x16x32_bf16 v[104:107], v[136:139], v[186:189], v[104:107]
	v_mfma_f32_16x16x32_bf16 v[120:123], v[136:139], v[160:163], v[120:123]
	v_mfma_f32_16x16x32_bf16 v[116:119], v[144:147], v[160:163], v[116:119]
	v_mfma_f32_16x16x32_bf16 v[100:103], v[144:147], v[186:189], v[100:103]
	v_mfma_f32_16x16x32_bf16 v[84:87], v[144:147], v[194:197], v[84:87]
	v_mfma_f32_16x16x32_bf16 v[68:71], v[144:147], v[202:205], v[68:71]
	v_mfma_f32_16x16x32_bf16 v[64:67], v[152:155], v[202:205], v[64:67]
	v_mfma_f32_16x16x32_bf16 v[76:79], v[152:155], v[194:197], v[76:79]
	v_mfma_f32_16x16x32_bf16 v[92:95], v[152:155], v[186:189], v[92:95]
	v_mfma_f32_16x16x32_bf16 v[108:111], v[152:155], v[160:163], v[108:111]
	v_mfma_f32_16x16x32_bf16 v[124:127], v[132:135], v[164:167], v[124:127]
	v_mfma_f32_16x16x32_bf16 v[112:115], v[132:135], v[190:193], v[112:115]
	v_mfma_f32_16x16x32_bf16 v[96:99], v[132:135], v[198:201], v[96:99]
	v_mfma_f32_16x16x32_bf16 v[80:83], v[132:135], v[206:209], v[80:83]
	v_mfma_f32_16x16x32_bf16 v[72:75], v[140:143], v[206:209], v[72:75]
	v_mfma_f32_16x16x32_bf16 v[88:91], v[140:143], v[198:201], v[88:91]
	v_mfma_f32_16x16x32_bf16 v[104:107], v[140:143], v[190:193], v[104:107]
	v_mfma_f32_16x16x32_bf16 v[120:123], v[140:143], v[164:167], v[120:123]
	v_mfma_f32_16x16x32_bf16 v[116:119], v[148:151], v[164:167], v[116:119]
	v_mfma_f32_16x16x32_bf16 v[100:103], v[148:151], v[190:193], v[100:103]
	v_mfma_f32_16x16x32_bf16 v[84:87], v[148:151], v[198:201], v[84:87]
	v_mfma_f32_16x16x32_bf16 v[68:71], v[148:151], v[206:209], v[68:71]
	v_mfma_f32_16x16x32_bf16 v[64:67], v[156:159], v[206:209], v[64:67]
	v_mfma_f32_16x16x32_bf16 v[76:79], v[156:159], v[198:201], v[76:79]
	v_mfma_f32_16x16x32_bf16 v[92:95], v[156:159], v[190:193], v[92:95]
	v_mfma_f32_16x16x32_bf16 v[108:111], v[156:159], v[164:167], v[108:111]
	s_barrier
	s_add_i32 s42, s42, s74
	v_lshl_add_u64 v[226:227], v[222:223], 0, s[10:11]
	s_mov_b32 m0, s42
	s_nop 0
	global_load_lds_dwordx4 v[226:227], off
	v_lshl_add_u64 v[226:227], v[222:223], 0, s[12:13]
	s_add_i32 m0, s42, 0x2000
	s_add_i32 s42, s43, s74
	global_load_lds_dwordx4 v[226:227], off
	v_lshl_add_u64 v[226:227], v[222:223], 0, s[14:15]
	s_mov_b32 m0, s42
	v_lshl_add_u64 v[222:223], v[222:223], 0, s[16:17]
	global_load_lds_dwordx4 v[226:227], off
	s_add_i32 m0, s42, 0x2000
	s_nop 0
	global_load_lds_dwordx4 v[222:223], off
	v_lshl_add_u64 v[222:223], v[224:225], 0, s[10:11]
	s_mov_b32 m0, s26
	s_nop 0
	global_load_lds_dwordx4 v[222:223], off
	v_lshl_add_u64 v[222:223], v[224:225], 0, s[12:13]
	s_mov_b32 m0, s27
	s_nop 0
	global_load_lds_dwordx4 v[222:223], off
	ds_read_b128 v[160:163], v221 offset:49152
	ds_read_b128 v[164:167], v221 offset:50176
	ds_read_b128 v[186:189], v221 offset:51200
	ds_read_b128 v[190:193], v221 offset:52224
	ds_read_b128 v[194:197], v221 offset:53248
	ds_read_b128 v[198:201], v221 offset:54272
	ds_read_b128 v[202:205], v221 offset:55296
	ds_read_b128 v[206:209], v221 offset:56320
	s_waitcnt vmcnt(8)
	s_waitcnt lgkmcnt(0)
	s_barrier
	s_waitcnt lgkmcnt(0)
	v_mfma_f32_16x16x32_bf16 v[60:63], v[128:131], v[160:163], v[60:63]
	v_mfma_f32_16x16x32_bf16 v[48:51], v[128:131], v[186:189], v[48:51]
	v_mfma_f32_16x16x32_bf16 v[32:35], v[128:131], v[194:197], v[32:35]
	v_mfma_f32_16x16x32_bf16 v[16:19], v[128:131], v[202:205], v[16:19]
	v_mfma_f32_16x16x32_bf16 v[8:11], v[136:139], v[202:205], v[8:11]
	v_mfma_f32_16x16x32_bf16 v[24:27], v[136:139], v[194:197], v[24:27]
	v_mfma_f32_16x16x32_bf16 v[40:43], v[136:139], v[186:189], v[40:43]
	v_mfma_f32_16x16x32_bf16 v[56:59], v[136:139], v[160:163], v[56:59]
	v_mfma_f32_16x16x32_bf16 v[52:55], v[144:147], v[160:163], v[52:55]
	v_mfma_f32_16x16x32_bf16 v[36:39], v[144:147], v[186:189], v[36:39]
	v_mfma_f32_16x16x32_bf16 v[20:23], v[144:147], v[194:197], v[20:23]
	v_mfma_f32_16x16x32_bf16 v[4:7], v[144:147], v[202:205], v[4:7]
	v_mfma_f32_16x16x32_bf16 v[0:3], v[152:155], v[202:205], v[0:3]
	v_mfma_f32_16x16x32_bf16 v[12:15], v[152:155], v[194:197], v[12:15]
	v_mfma_f32_16x16x32_bf16 v[28:31], v[152:155], v[186:189], v[28:31]
	v_mfma_f32_16x16x32_bf16 v[44:47], v[152:155], v[160:163], v[44:47]
	v_mfma_f32_16x16x32_bf16 v[60:63], v[132:135], v[164:167], v[60:63]
	v_mfma_f32_16x16x32_bf16 v[48:51], v[132:135], v[190:193], v[48:51]
	v_mfma_f32_16x16x32_bf16 v[32:35], v[132:135], v[198:201], v[32:35]
	v_mfma_f32_16x16x32_bf16 v[16:19], v[132:135], v[206:209], v[16:19]
	v_mfma_f32_16x16x32_bf16 v[8:11], v[140:143], v[206:209], v[8:11]
	v_mfma_f32_16x16x32_bf16 v[24:27], v[140:143], v[198:201], v[24:27]
	v_mfma_f32_16x16x32_bf16 v[40:43], v[140:143], v[190:193], v[40:43]
	v_mfma_f32_16x16x32_bf16 v[56:59], v[140:143], v[164:167], v[56:59]
	v_mfma_f32_16x16x32_bf16 v[52:55], v[148:151], v[164:167], v[52:55]
	v_mfma_f32_16x16x32_bf16 v[36:39], v[148:151], v[190:193], v[36:39]
	v_mfma_f32_16x16x32_bf16 v[20:23], v[148:151], v[198:201], v[20:23]
	v_mfma_f32_16x16x32_bf16 v[4:7], v[148:151], v[206:209], v[4:7]
	v_mfma_f32_16x16x32_bf16 v[0:3], v[156:159], v[206:209], v[0:3]
	v_mfma_f32_16x16x32_bf16 v[12:15], v[156:159], v[198:201], v[12:15]
	v_mfma_f32_16x16x32_bf16 v[28:31], v[156:159], v[190:193], v[28:31]
	v_mfma_f32_16x16x32_bf16 v[44:47], v[156:159], v[164:167], v[44:47]
	s_barrier
	s_cmp_gt_u32 s70, 13
	s_cbranch_scc0 .LBB0_386
	s_and_b64 vcc, exec, s[58:59]
	s_cbranch_vccz .LBB0_389
	s_barrier

.LBB0_760:
	s_add_i32 s78, s78, 2
	s_mov_b32 s50, s78
	s_ashr_i32 s51, s50, 31
	s_lshl_b64 s[80:81], s[50:51], 7
	s_add_u32 s51, s80, 0x100
	s_addc_u32 s79, s81, 0
	s_add_u32 s82, s48, s51
	s_addc_u32 s83, s49, s79
	s_add_u32 s84, s8, s51
	s_addc_u32 s79, s9, s79
	s_add_i32 s85, 0, 0x10000
	s_cmp_eq_u32 s50, 14
	s_cselect_b32 s51, s35, s83
	s_cselect_b32 s50, s76, s82
	s_cselect_b32 s83, s31, s79
	s_cselect_b32 s82, s77, s84
	s_add_i32 s79, 0, 0x14000
	s_add_u32 s80, s48, s80
	s_addc_u32 s81, s49, s81
	v_lshl_add_u64 v[134:135], s[80:81], 0, v[128:129]
	v_lshl_add_u64 v[224:225], v[134:135], 0, s[14:15]
	s_add_i32 m0, s62, 0xc000
	s_nop 0
	global_load_lds_dwordx4 v[224:225], off
	v_lshl_add_u64 v[134:135], v[134:135], 0, s[16:17]
	s_add_i32 m0, s62, 0xe000
	s_nop 0
	global_load_lds_dwordx4 v[134:135], off
	v_add_u32_e32 v134, s85, v137
	ds_read_b128 v[130:133], v134
	ds_read_b128 v[140:143], v134 offset:1024
	ds_read_b128 v[144:147], v134 offset:2048
	ds_read_b128 v[148:151], v134 offset:3072
	v_add_u32_e32 v134, s79, v137
	ds_read_b128 v[152:155], v134
	ds_read_b128 v[156:159], v134 offset:1024
	ds_read_b128 v[160:163], v134 offset:2048
	ds_read_b128 v[164:167], v134 offset:3072
	ds_read_b128 v[182:185], v138
	ds_read_b128 v[186:189], v138 offset:1024
	ds_read_b128 v[190:193], v138 offset:2048
	ds_read_b128 v[194:197], v138 offset:3072
	ds_read_b128 v[198:201], v138 offset:4096
	ds_read_b128 v[202:205], v138 offset:5120
	ds_read_b128 v[206:209], v138 offset:6144
	ds_read_b128 v[220:223], v138 offset:7168
	s_nop 0
	s_waitcnt vmcnt(8)
	s_waitcnt lgkmcnt(0)
	s_barrier
	s_waitcnt lgkmcnt(0)
	v_mfma_f32_16x16x32_bf16 v[124:127], v[130:133], v[182:185], v[124:127]
	v_mfma_f32_16x16x32_bf16 v[108:111], v[130:133], v[190:193], v[108:111]
	v_mfma_f32_16x16x32_bf16 v[92:95], v[130:133], v[198:201], v[92:95]
	v_mfma_f32_16x16x32_bf16 v[76:79], v[130:133], v[206:209], v[76:79]
	v_mfma_f32_16x16x32_bf16 v[72:75], v[144:147], v[206:209], v[72:75]
	v_mfma_f32_16x16x32_bf16 v[88:91], v[144:147], v[198:201], v[88:91]
	v_mfma_f32_16x16x32_bf16 v[104:107], v[144:147], v[190:193], v[104:107]
	v_mfma_f32_16x16x32_bf16 v[120:123], v[144:147], v[182:185], v[120:123]
	v_mfma_f32_16x16x32_bf16 v[116:119], v[152:155], v[182:185], v[116:119]
	v_mfma_f32_16x16x32_bf16 v[100:103], v[152:155], v[190:193], v[100:103]
	v_mfma_f32_16x16x32_bf16 v[84:87], v[152:155], v[198:201], v[84:87]
	v_mfma_f32_16x16x32_bf16 v[68:71], v[152:155], v[206:209], v[68:71]
	v_mfma_f32_16x16x32_bf16 v[64:67], v[160:163], v[206:209], v[64:67]
	v_mfma_f32_16x16x32_bf16 v[80:83], v[160:163], v[198:201], v[80:83]
	v_mfma_f32_16x16x32_bf16 v[96:99], v[160:163], v[190:193], v[96:99]
	v_mfma_f32_16x16x32_bf16 v[112:115], v[160:163], v[182:185], v[112:115]
	v_mfma_f32_16x16x32_bf16 v[124:127], v[140:143], v[186:189], v[124:127]
	v_mfma_f32_16x16x32_bf16 v[108:111], v[140:143], v[194:197], v[108:111]
	v_mfma_f32_16x16x32_bf16 v[92:95], v[140:143], v[202:205], v[92:95]
	v_mfma_f32_16x16x32_bf16 v[76:79], v[140:143], v[220:223], v[76:79]
	v_mfma_f32_16x16x32_bf16 v[72:75], v[148:151], v[220:223], v[72:75]
	v_mfma_f32_16x16x32_bf16 v[88:91], v[148:151], v[202:205], v[88:91]
	v_mfma_f32_16x16x32_bf16 v[104:107], v[148:151], v[194:197], v[104:107]
	v_mfma_f32_16x16x32_bf16 v[120:123], v[148:151], v[186:189], v[120:123]
	v_mfma_f32_16x16x32_bf16 v[116:119], v[156:159], v[186:189], v[116:119]
	v_mfma_f32_16x16x32_bf16 v[100:103], v[156:159], v[194:197], v[100:103]
	v_mfma_f32_16x16x32_bf16 v[84:87], v[156:159], v[202:205], v[84:87]
	v_mfma_f32_16x16x32_bf16 v[68:71], v[156:159], v[220:223], v[68:71]
	v_mfma_f32_16x16x32_bf16 v[64:67], v[164:167], v[220:223], v[64:67]
	v_mfma_f32_16x16x32_bf16 v[80:83], v[164:167], v[202:205], v[80:83]
	v_mfma_f32_16x16x32_bf16 v[96:99], v[164:167], v[194:197], v[96:99]
	v_mfma_f32_16x16x32_bf16 v[112:115], v[164:167], v[186:189], v[112:115]
	s_barrier
	s_add_i32 s80, s85, s59
	v_lshl_add_u64 v[134:135], s[82:83], 0, v[172:173]
	s_mov_b32 m0, s80
	s_nop 0
	global_load_lds_dwordx4 v[134:135], off
	v_lshl_add_u64 v[224:225], v[134:135], 0, s[40:41]
	s_add_i32 m0, s80, 0x2000
	s_add_i32 s79, s79, s59
	global_load_lds_dwordx4 v[224:225], off
	v_lshl_add_u64 v[224:225], v[134:135], 0, s[4:5]
	s_mov_b32 m0, s79
	s_nop 0
	global_load_lds_dwordx4 v[224:225], off
	v_lshl_add_u64 v[224:225], v[134:135], 0, s[6:7]
	s_add_i32 m0, s79, 0x2000
	s_nop 0
	global_load_lds_dwordx4 v[224:225], off
	v_lshl_add_u64 v[224:225], s[50:51], 0, v[128:129]
	s_mov_b32 m0, s62
	v_lshl_add_u64 v[226:227], v[224:225], 0, s[40:41]
	global_load_lds_dwordx4 v[224:225], off
	s_mov_b32 m0, s63
	s_nop 0
	global_load_lds_dwordx4 v[226:227], off
	ds_read_b128 v[182:185], v138 offset:16384
	ds_read_b128 v[186:189], v138 offset:17408
	ds_read_b128 v[190:193], v138 offset:18432
	ds_read_b128 v[194:197], v138 offset:19456
	ds_read_b128 v[198:201], v138 offset:20480
	ds_read_b128 v[202:205], v138 offset:21504
	ds_read_b128 v[206:209], v138 offset:22528
	ds_read_b128 v[220:223], v138 offset:23552
	s_waitcnt vmcnt(8)
	s_waitcnt lgkmcnt(0)
	s_barrier
	s_waitcnt lgkmcnt(0)
	v_mfma_f32_16x16x32_bf16 v[60:63], v[130:133], v[182:185], v[60:63]
	v_mfma_f32_16x16x32_bf16 v[44:47], v[130:133], v[190:193], v[44:47]
	v_mfma_f32_16x16x32_bf16 v[28:31], v[130:133], v[198:201], v[28:31]
	v_mfma_f32_16x16x32_bf16 v[12:15], v[130:133], v[206:209], v[12:15]
	v_mfma_f32_16x16x32_bf16 v[8:11], v[144:147], v[206:209], v[8:11]
	v_mfma_f32_16x16x32_bf16 v[24:27], v[144:147], v[198:201], v[24:27]
	v_mfma_f32_16x16x32_bf16 v[40:43], v[144:147], v[190:193], v[40:43]
	v_mfma_f32_16x16x32_bf16 v[56:59], v[144:147], v[182:185], v[56:59]
	v_mfma_f32_16x16x32_bf16 v[52:55], v[152:155], v[182:185], v[52:55]
	v_mfma_f32_16x16x32_bf16 v[36:39], v[152:155], v[190:193], v[36:39]
	v_mfma_f32_16x16x32_bf16 v[20:23], v[152:155], v[198:201], v[20:23]
	v_mfma_f32_16x16x32_bf16 v[4:7], v[152:155], v[206:209], v[4:7]
	v_mfma_f32_16x16x32_bf16 v[0:3], v[160:163], v[206:209], v[0:3]
	v_mfma_f32_16x16x32_bf16 v[16:19], v[160:163], v[198:201], v[16:19]
	v_mfma_f32_16x16x32_bf16 v[32:35], v[160:163], v[190:193], v[32:35]
	v_mfma_f32_16x16x32_bf16 v[48:51], v[160:163], v[182:185], v[48:51]
	v_mfma_f32_16x16x32_bf16 v[60:63], v[140:143], v[186:189], v[60:63]
	v_mfma_f32_16x16x32_bf16 v[44:47], v[140:143], v[194:197], v[44:47]
	v_mfma_f32_16x16x32_bf16 v[28:31], v[140:143], v[202:205], v[28:31]
	v_mfma_f32_16x16x32_bf16 v[12:15], v[140:143], v[220:223], v[12:15]
	v_mfma_f32_16x16x32_bf16 v[8:11], v[148:151], v[220:223], v[8:11]
	v_mfma_f32_16x16x32_bf16 v[24:27], v[148:151], v[202:205], v[24:27]
	v_mfma_f32_16x16x32_bf16 v[40:43], v[148:151], v[194:197], v[40:43]
	v_mfma_f32_16x16x32_bf16 v[56:59], v[148:151], v[186:189], v[56:59]
	v_mfma_f32_16x16x32_bf16 v[52:55], v[156:159], v[186:189], v[52:55]
	v_mfma_f32_16x16x32_bf16 v[36:39], v[156:159], v[194:197], v[36:39]
	v_mfma_f32_16x16x32_bf16 v[20:23], v[156:159], v[202:205], v[20:23]
	v_mfma_f32_16x16x32_bf16 v[4:7], v[156:159], v[220:223], v[4:7]
	v_mfma_f32_16x16x32_bf16 v[0:3], v[164:167], v[220:223], v[0:3]
	v_mfma_f32_16x16x32_bf16 v[16:19], v[164:167], v[202:205], v[16:19]
	v_mfma_f32_16x16x32_bf16 v[32:35], v[164:167], v[194:197], v[32:35]
	v_mfma_f32_16x16x32_bf16 v[48:51], v[164:167], v[186:189], v[48:51]
	s_barrier
	s_mov_b32 m0, s68
	v_lshl_add_u64 v[226:227], v[224:225], 0, s[4:5]
	global_load_lds_dwordx4 v[226:227], off
	v_lshl_add_u64 v[226:227], v[224:225], 0, s[6:7]
	s_mov_b32 m0, s69
	s_nop 0
	global_load_lds_dwordx4 v[226:227], off
	s_add_i32 s50, 0, 0x18000
	v_add_u32_e32 v139, s50, v137
	s_add_i32 s51, 0, 0x1c000
	ds_read_b128 v[130:133], v139
	ds_read_b128 v[140:143], v139 offset:1024
	ds_read_b128 v[144:147], v139 offset:2048
	ds_read_b128 v[148:151], v139 offset:3072
	v_add_u32_e32 v139, s51, v137
	ds_read_b128 v[152:155], v139
	ds_read_b128 v[156:159], v139 offset:1024
	ds_read_b128 v[160:163], v139 offset:2048
	ds_read_b128 v[164:167], v139 offset:3072
	ds_read_b128 v[182:185], v138 offset:32768
	ds_read_b128 v[186:189], v138 offset:33792
	ds_read_b128 v[190:193], v138 offset:34816
	ds_read_b128 v[194:197], v138 offset:35840
	ds_read_b128 v[198:201], v138 offset:36864
	ds_read_b128 v[202:205], v138 offset:37888
	ds_read_b128 v[206:209], v138 offset:38912
	ds_read_b128 v[220:223], v138 offset:39936
	s_nop 0
	s_waitcnt vmcnt(8)
	s_waitcnt lgkmcnt(0)
	s_barrier
	s_waitcnt lgkmcnt(0)
	v_mfma_f32_16x16x32_bf16 v[124:127], v[130:133], v[182:185], v[124:127]
	v_mfma_f32_16x16x32_bf16 v[108:111], v[130:133], v[190:193], v[108:111]
	v_mfma_f32_16x16x32_bf16 v[92:95], v[130:133], v[198:201], v[92:95]
	v_mfma_f32_16x16x32_bf16 v[76:79], v[130:133], v[206:209], v[76:79]
	v_mfma_f32_16x16x32_bf16 v[72:75], v[144:147], v[206:209], v[72:75]
	v_mfma_f32_16x16x32_bf16 v[88:91], v[144:147], v[198:201], v[88:91]
	v_mfma_f32_16x16x32_bf16 v[104:107], v[144:147], v[190:193], v[104:107]
	v_mfma_f32_16x16x32_bf16 v[120:123], v[144:147], v[182:185], v[120:123]
	v_mfma_f32_16x16x32_bf16 v[116:119], v[152:155], v[182:185], v[116:119]
	v_mfma_f32_16x16x32_bf16 v[100:103], v[152:155], v[190:193], v[100:103]
	v_mfma_f32_16x16x32_bf16 v[84:87], v[152:155], v[198:201], v[84:87]
	v_mfma_f32_16x16x32_bf16 v[68:71], v[152:155], v[206:209], v[68:71]
	v_mfma_f32_16x16x32_bf16 v[64:67], v[160:163], v[206:209], v[64:67]
	v_mfma_f32_16x16x32_bf16 v[80:83], v[160:163], v[198:201], v[80:83]
	v_mfma_f32_16x16x32_bf16 v[96:99], v[160:163], v[190:193], v[96:99]
	v_mfma_f32_16x16x32_bf16 v[112:115], v[160:163], v[182:185], v[112:115]
	v_mfma_f32_16x16x32_bf16 v[124:127], v[140:143], v[186:189], v[124:127]
	v_mfma_f32_16x16x32_bf16 v[108:111], v[140:143], v[194:197], v[108:111]
	v_mfma_f32_16x16x32_bf16 v[92:95], v[140:143], v[202:205], v[92:95]
	v_mfma_f32_16x16x32_bf16 v[76:79], v[140:143], v[220:223], v[76:79]
	v_mfma_f32_16x16x32_bf16 v[72:75], v[148:151], v[220:223], v[72:75]
	v_mfma_f32_16x16x32_bf16 v[88:91], v[148:151], v[202:205], v[88:91]
	v_mfma_f32_16x16x32_bf16 v[104:107], v[148:151], v[194:197], v[104:107]
	v_mfma_f32_16x16x32_bf16 v[120:123], v[148:151], v[186:189], v[120:123]
	v_mfma_f32_16x16x32_bf16 v[116:119], v[156:159], v[186:189], v[116:119]
	v_mfma_f32_16x16x32_bf16 v[100:103], v[156:159], v[194:197], v[100:103]
	v_mfma_f32_16x16x32_bf16 v[84:87], v[156:159], v[202:205], v[84:87]
	v_mfma_f32_16x16x32_bf16 v[68:71], v[156:159], v[220:223], v[68:71]
	v_mfma_f32_16x16x32_bf16 v[64:67], v[164:167], v[220:223], v[64:67]
	v_mfma_f32_16x16x32_bf16 v[80:83], v[164:167], v[202:205], v[80:83]
	v_mfma_f32_16x16x32_bf16 v[96:99], v[164:167], v[194:197], v[96:99]
	v_mfma_f32_16x16x32_bf16 v[112:115], v[164:167], v[186:189], v[112:115]
	s_barrier
	s_add_i32 s50, s50, s59
	v_lshl_add_u64 v[226:227], v[134:135], 0, s[10:11]
	s_mov_b32 m0, s50
	s_nop 0
	global_load_lds_dwordx4 v[226:227], off
	v_lshl_add_u64 v[226:227], v[134:135], 0, s[12:13]
	s_add_i32 m0, s50, 0x2000
	s_add_i32 s50, s51, s59
	global_load_lds_dwordx4 v[226:227], off
	v_lshl_add_u64 v[226:227], v[134:135], 0, s[14:15]
	s_mov_b32 m0, s50
	v_lshl_add_u64 v[134:135], v[134:135], 0, s[16:17]
	global_load_lds_dwordx4 v[226:227], off
	s_add_i32 m0, s50, 0x2000
	s_nop 0
	global_load_lds_dwordx4 v[134:135], off
	v_lshl_add_u64 v[134:135], v[224:225], 0, s[10:11]
	s_mov_b32 m0, s72
	s_nop 0
	global_load_lds_dwordx4 v[134:135], off
	v_lshl_add_u64 v[134:135], v[224:225], 0, s[12:13]
	s_mov_b32 m0, s73
	s_nop 0
	global_load_lds_dwordx4 v[134:135], off
	ds_read_b128 v[182:185], v138 offset:49152
	ds_read_b128 v[186:189], v138 offset:50176
	ds_read_b128 v[190:193], v138 offset:51200
	ds_read_b128 v[194:197], v138 offset:52224
	ds_read_b128 v[198:201], v138 offset:53248
	ds_read_b128 v[202:205], v138 offset:54272
	ds_read_b128 v[206:209], v138 offset:55296
	ds_read_b128 v[220:223], v138 offset:56320
	s_waitcnt vmcnt(8)
	s_waitcnt lgkmcnt(0)
	s_barrier
	s_waitcnt lgkmcnt(0)
	v_mfma_f32_16x16x32_bf16 v[60:63], v[130:133], v[182:185], v[60:63]
	v_mfma_f32_16x16x32_bf16 v[44:47], v[130:133], v[190:193], v[44:47]
	v_mfma_f32_16x16x32_bf16 v[28:31], v[130:133], v[198:201], v[28:31]
	v_mfma_f32_16x16x32_bf16 v[12:15], v[130:133], v[206:209], v[12:15]
	v_mfma_f32_16x16x32_bf16 v[8:11], v[144:147], v[206:209], v[8:11]
	v_mfma_f32_16x16x32_bf16 v[24:27], v[144:147], v[198:201], v[24:27]
	v_mfma_f32_16x16x32_bf16 v[40:43], v[144:147], v[190:193], v[40:43]
	v_mfma_f32_16x16x32_bf16 v[56:59], v[144:147], v[182:185], v[56:59]
	v_mfma_f32_16x16x32_bf16 v[52:55], v[152:155], v[182:185], v[52:55]
	v_mfma_f32_16x16x32_bf16 v[36:39], v[152:155], v[190:193], v[36:39]
	v_mfma_f32_16x16x32_bf16 v[20:23], v[152:155], v[198:201], v[20:23]
	v_mfma_f32_16x16x32_bf16 v[4:7], v[152:155], v[206:209], v[4:7]
	v_mfma_f32_16x16x32_bf16 v[0:3], v[160:163], v[206:209], v[0:3]
	v_mfma_f32_16x16x32_bf16 v[16:19], v[160:163], v[198:201], v[16:19]
	v_mfma_f32_16x16x32_bf16 v[32:35], v[160:163], v[190:193], v[32:35]
	v_mfma_f32_16x16x32_bf16 v[48:51], v[160:163], v[182:185], v[48:51]
	v_mfma_f32_16x16x32_bf16 v[60:63], v[140:143], v[186:189], v[60:63]
	v_mfma_f32_16x16x32_bf16 v[44:47], v[140:143], v[194:197], v[44:47]
	v_mfma_f32_16x16x32_bf16 v[28:31], v[140:143], v[202:205], v[28:31]
	v_mfma_f32_16x16x32_bf16 v[12:15], v[140:143], v[220:223], v[12:15]
	v_mfma_f32_16x16x32_bf16 v[8:11], v[148:151], v[220:223], v[8:11]
	v_mfma_f32_16x16x32_bf16 v[24:27], v[148:151], v[202:205], v[24:27]
	v_mfma_f32_16x16x32_bf16 v[40:43], v[148:151], v[194:197], v[40:43]
	v_mfma_f32_16x16x32_bf16 v[56:59], v[148:151], v[186:189], v[56:59]
	v_mfma_f32_16x16x32_bf16 v[52:55], v[156:159], v[186:189], v[52:55]
	v_mfma_f32_16x16x32_bf16 v[36:39], v[156:159], v[194:197], v[36:39]
	v_mfma_f32_16x16x32_bf16 v[20:23], v[156:159], v[202:205], v[20:23]
	v_mfma_f32_16x16x32_bf16 v[4:7], v[156:159], v[220:223], v[4:7]
	v_mfma_f32_16x16x32_bf16 v[0:3], v[164:167], v[220:223], v[0:3]
	v_mfma_f32_16x16x32_bf16 v[16:19], v[164:167], v[202:205], v[16:19]
	v_mfma_f32_16x16x32_bf16 v[32:35], v[164:167], v[194:197], v[32:35]
	v_mfma_f32_16x16x32_bf16 v[48:51], v[164:167], v[186:189], v[48:51]
	s_barrier
	s_cmp_gt_u32 s78, 13
	s_cbranch_scc0 .LBB0_760
	s_and_b64 vcc, exec, s[28:29]
	s_cbranch_vccz .LBB0_763
	s_barrier

.LBB0_784:
	s_add_i32 s80, s80, 2
	s_mov_b32 s48, s80
	s_ashr_i32 s49, s48, 31
	s_lshl_b64 s[82:83], s[48:49], 7
	s_add_u32 s49, s82, 0x100
	s_addc_u32 s81, s83, 0
	s_add_u32 s84, s42, s49
	s_addc_u32 s85, s43, s81
	s_add_u32 s86, s8, s49
	s_addc_u32 s81, s9, s81
	s_add_i32 s87, 0, 0x10000
	s_cmp_eq_u32 s48, 14
	s_cselect_b32 s49, s39, s85
	s_cselect_b32 s48, s72, s84
	s_cselect_b32 s85, s35, s81
	s_cselect_b32 s84, s73, s86
	s_add_i32 s81, 0, 0x14000
	s_add_u32 s82, s42, s82
	s_addc_u32 s83, s43, s83
	v_lshl_add_u64 v[134:135], s[82:83], 0, v[128:129]
	v_lshl_add_u64 v[224:225], v[134:135], 0, s[14:15]
	s_add_i32 m0, s74, 0xc000
	s_nop 0
	global_load_lds_dwordx4 v[224:225], off
	v_lshl_add_u64 v[134:135], v[134:135], 0, s[16:17]
	s_add_i32 m0, s74, 0xe000
	s_nop 0
	global_load_lds_dwordx4 v[134:135], off
	v_add_u32_e32 v134, s87, v137
	ds_read_b128 v[130:133], v134
	ds_read_b128 v[140:143], v134 offset:1024
	ds_read_b128 v[144:147], v134 offset:2048
	ds_read_b128 v[148:151], v134 offset:3072
	v_add_u32_e32 v134, s81, v137
	ds_read_b128 v[152:155], v134
	ds_read_b128 v[156:159], v134 offset:1024
	ds_read_b128 v[160:163], v134 offset:2048
	ds_read_b128 v[164:167], v134 offset:3072
	ds_read_b128 v[182:185], v138
	ds_read_b128 v[186:189], v138 offset:1024
	ds_read_b128 v[190:193], v138 offset:2048
	ds_read_b128 v[194:197], v138 offset:3072
	ds_read_b128 v[198:201], v138 offset:4096
	ds_read_b128 v[202:205], v138 offset:5120
	ds_read_b128 v[206:209], v138 offset:6144
	ds_read_b128 v[220:223], v138 offset:7168
	s_nop 0
	s_waitcnt vmcnt(8)
	s_waitcnt lgkmcnt(0)
	s_barrier
	s_waitcnt lgkmcnt(0)
	v_mfma_f32_16x16x32_bf16 v[124:127], v[130:133], v[182:185], v[124:127]
	v_mfma_f32_16x16x32_bf16 v[108:111], v[130:133], v[190:193], v[108:111]
	v_mfma_f32_16x16x32_bf16 v[92:95], v[130:133], v[198:201], v[92:95]
	v_mfma_f32_16x16x32_bf16 v[76:79], v[130:133], v[206:209], v[76:79]
	v_mfma_f32_16x16x32_bf16 v[72:75], v[144:147], v[206:209], v[72:75]
	v_mfma_f32_16x16x32_bf16 v[88:91], v[144:147], v[198:201], v[88:91]
	v_mfma_f32_16x16x32_bf16 v[104:107], v[144:147], v[190:193], v[104:107]
	v_mfma_f32_16x16x32_bf16 v[120:123], v[144:147], v[182:185], v[120:123]
	v_mfma_f32_16x16x32_bf16 v[116:119], v[152:155], v[182:185], v[116:119]
	v_mfma_f32_16x16x32_bf16 v[100:103], v[152:155], v[190:193], v[100:103]
	v_mfma_f32_16x16x32_bf16 v[84:87], v[152:155], v[198:201], v[84:87]
	v_mfma_f32_16x16x32_bf16 v[68:71], v[152:155], v[206:209], v[68:71]
	v_mfma_f32_16x16x32_bf16 v[64:67], v[160:163], v[206:209], v[64:67]
	v_mfma_f32_16x16x32_bf16 v[80:83], v[160:163], v[198:201], v[80:83]
	v_mfma_f32_16x16x32_bf16 v[96:99], v[160:163], v[190:193], v[96:99]
	v_mfma_f32_16x16x32_bf16 v[112:115], v[160:163], v[182:185], v[112:115]
	v_mfma_f32_16x16x32_bf16 v[124:127], v[140:143], v[186:189], v[124:127]
	v_mfma_f32_16x16x32_bf16 v[108:111], v[140:143], v[194:197], v[108:111]
	v_mfma_f32_16x16x32_bf16 v[92:95], v[140:143], v[202:205], v[92:95]
	v_mfma_f32_16x16x32_bf16 v[76:79], v[140:143], v[220:223], v[76:79]
	v_mfma_f32_16x16x32_bf16 v[72:75], v[148:151], v[220:223], v[72:75]
	v_mfma_f32_16x16x32_bf16 v[88:91], v[148:151], v[202:205], v[88:91]
	v_mfma_f32_16x16x32_bf16 v[104:107], v[148:151], v[194:197], v[104:107]
	v_mfma_f32_16x16x32_bf16 v[120:123], v[148:151], v[186:189], v[120:123]
	v_mfma_f32_16x16x32_bf16 v[116:119], v[156:159], v[186:189], v[116:119]
	v_mfma_f32_16x16x32_bf16 v[100:103], v[156:159], v[194:197], v[100:103]
	v_mfma_f32_16x16x32_bf16 v[84:87], v[156:159], v[202:205], v[84:87]
	v_mfma_f32_16x16x32_bf16 v[68:71], v[156:159], v[220:223], v[68:71]
	v_mfma_f32_16x16x32_bf16 v[64:67], v[164:167], v[220:223], v[64:67]
	v_mfma_f32_16x16x32_bf16 v[80:83], v[164:167], v[202:205], v[80:83]
	v_mfma_f32_16x16x32_bf16 v[96:99], v[164:167], v[194:197], v[96:99]
	v_mfma_f32_16x16x32_bf16 v[112:115], v[164:167], v[186:189], v[112:115]
	s_barrier
	s_add_i32 s82, s87, s63
	v_lshl_add_u64 v[134:135], s[84:85], 0, v[172:173]
	s_mov_b32 m0, s82
	s_nop 0
	global_load_lds_dwordx4 v[134:135], off
	v_lshl_add_u64 v[224:225], v[134:135], 0, s[40:41]
	s_add_i32 m0, s82, 0x2000
	s_add_i32 s81, s81, s63
	global_load_lds_dwordx4 v[224:225], off
	v_lshl_add_u64 v[224:225], v[134:135], 0, s[4:5]
	s_mov_b32 m0, s81
	s_nop 0
	global_load_lds_dwordx4 v[224:225], off
	v_lshl_add_u64 v[224:225], v[134:135], 0, s[6:7]
	s_add_i32 m0, s81, 0x2000
	s_nop 0
	global_load_lds_dwordx4 v[224:225], off
	v_lshl_add_u64 v[224:225], s[48:49], 0, v[128:129]
	s_mov_b32 m0, s74
	v_lshl_add_u64 v[226:227], v[224:225], 0, s[40:41]
	global_load_lds_dwordx4 v[224:225], off
	s_mov_b32 m0, s75
	s_nop 0
	global_load_lds_dwordx4 v[226:227], off
	ds_read_b128 v[182:185], v138 offset:16384
	ds_read_b128 v[186:189], v138 offset:17408
	ds_read_b128 v[190:193], v138 offset:18432
	ds_read_b128 v[194:197], v138 offset:19456
	ds_read_b128 v[198:201], v138 offset:20480
	ds_read_b128 v[202:205], v138 offset:21504
	ds_read_b128 v[206:209], v138 offset:22528
	ds_read_b128 v[220:223], v138 offset:23552
	s_waitcnt vmcnt(8)
	s_waitcnt lgkmcnt(0)
	s_barrier
	s_waitcnt lgkmcnt(0)
	v_mfma_f32_16x16x32_bf16 v[60:63], v[130:133], v[182:185], v[60:63]
	v_mfma_f32_16x16x32_bf16 v[44:47], v[130:133], v[190:193], v[44:47]
	v_mfma_f32_16x16x32_bf16 v[28:31], v[130:133], v[198:201], v[28:31]
	v_mfma_f32_16x16x32_bf16 v[12:15], v[130:133], v[206:209], v[12:15]
	v_mfma_f32_16x16x32_bf16 v[8:11], v[144:147], v[206:209], v[8:11]
	v_mfma_f32_16x16x32_bf16 v[24:27], v[144:147], v[198:201], v[24:27]
	v_mfma_f32_16x16x32_bf16 v[40:43], v[144:147], v[190:193], v[40:43]
	v_mfma_f32_16x16x32_bf16 v[56:59], v[144:147], v[182:185], v[56:59]
	v_mfma_f32_16x16x32_bf16 v[52:55], v[152:155], v[182:185], v[52:55]
	v_mfma_f32_16x16x32_bf16 v[36:39], v[152:155], v[190:193], v[36:39]
	v_mfma_f32_16x16x32_bf16 v[20:23], v[152:155], v[198:201], v[20:23]
	v_mfma_f32_16x16x32_bf16 v[4:7], v[152:155], v[206:209], v[4:7]
	v_mfma_f32_16x16x32_bf16 v[0:3], v[160:163], v[206:209], v[0:3]
	v_mfma_f32_16x16x32_bf16 v[16:19], v[160:163], v[198:201], v[16:19]
	v_mfma_f32_16x16x32_bf16 v[32:35], v[160:163], v[190:193], v[32:35]
	v_mfma_f32_16x16x32_bf16 v[48:51], v[160:163], v[182:185], v[48:51]
	v_mfma_f32_16x16x32_bf16 v[60:63], v[140:143], v[186:189], v[60:63]
	v_mfma_f32_16x16x32_bf16 v[44:47], v[140:143], v[194:197], v[44:47]
	v_mfma_f32_16x16x32_bf16 v[28:31], v[140:143], v[202:205], v[28:31]
	v_mfma_f32_16x16x32_bf16 v[12:15], v[140:143], v[220:223], v[12:15]
	v_mfma_f32_16x16x32_bf16 v[8:11], v[148:151], v[220:223], v[8:11]
	v_mfma_f32_16x16x32_bf16 v[24:27], v[148:151], v[202:205], v[24:27]
	v_mfma_f32_16x16x32_bf16 v[40:43], v[148:151], v[194:197], v[40:43]
	v_mfma_f32_16x16x32_bf16 v[56:59], v[148:151], v[186:189], v[56:59]
	v_mfma_f32_16x16x32_bf16 v[52:55], v[156:159], v[186:189], v[52:55]
	v_mfma_f32_16x16x32_bf16 v[36:39], v[156:159], v[194:197], v[36:39]
	v_mfma_f32_16x16x32_bf16 v[20:23], v[156:159], v[202:205], v[20:23]
	v_mfma_f32_16x16x32_bf16 v[4:7], v[156:159], v[220:223], v[4:7]
	v_mfma_f32_16x16x32_bf16 v[0:3], v[164:167], v[220:223], v[0:3]
	v_mfma_f32_16x16x32_bf16 v[16:19], v[164:167], v[202:205], v[16:19]
	v_mfma_f32_16x16x32_bf16 v[32:35], v[164:167], v[194:197], v[32:35]
	v_mfma_f32_16x16x32_bf16 v[48:51], v[164:167], v[186:189], v[48:51]
	s_barrier
	s_mov_b32 m0, s76
	v_lshl_add_u64 v[226:227], v[224:225], 0, s[4:5]
	global_load_lds_dwordx4 v[226:227], off
	v_lshl_add_u64 v[226:227], v[224:225], 0, s[6:7]
	s_mov_b32 m0, s77
	s_nop 0
	global_load_lds_dwordx4 v[226:227], off
	s_add_i32 s48, 0, 0x18000
	v_add_u32_e32 v139, s48, v137
	s_add_i32 s49, 0, 0x1c000
	ds_read_b128 v[130:133], v139
	ds_read_b128 v[140:143], v139 offset:1024
	ds_read_b128 v[144:147], v139 offset:2048
	ds_read_b128 v[148:151], v139 offset:3072
	v_add_u32_e32 v139, s49, v137
	ds_read_b128 v[152:155], v139
	ds_read_b128 v[156:159], v139 offset:1024
	ds_read_b128 v[160:163], v139 offset:2048
	ds_read_b128 v[164:167], v139 offset:3072
	ds_read_b128 v[182:185], v138 offset:32768
	ds_read_b128 v[186:189], v138 offset:33792
	ds_read_b128 v[190:193], v138 offset:34816
	ds_read_b128 v[194:197], v138 offset:35840
	ds_read_b128 v[198:201], v138 offset:36864
	ds_read_b128 v[202:205], v138 offset:37888
	ds_read_b128 v[206:209], v138 offset:38912
	ds_read_b128 v[220:223], v138 offset:39936
	s_nop 0
	s_waitcnt vmcnt(8)
	s_waitcnt lgkmcnt(0)
	s_barrier
	s_waitcnt lgkmcnt(0)
	v_mfma_f32_16x16x32_bf16 v[124:127], v[130:133], v[182:185], v[124:127]
	v_mfma_f32_16x16x32_bf16 v[108:111], v[130:133], v[190:193], v[108:111]
	v_mfma_f32_16x16x32_bf16 v[92:95], v[130:133], v[198:201], v[92:95]
	v_mfma_f32_16x16x32_bf16 v[76:79], v[130:133], v[206:209], v[76:79]
	v_mfma_f32_16x16x32_bf16 v[72:75], v[144:147], v[206:209], v[72:75]
	v_mfma_f32_16x16x32_bf16 v[88:91], v[144:147], v[198:201], v[88:91]
	v_mfma_f32_16x16x32_bf16 v[104:107], v[144:147], v[190:193], v[104:107]
	v_mfma_f32_16x16x32_bf16 v[120:123], v[144:147], v[182:185], v[120:123]
	v_mfma_f32_16x16x32_bf16 v[116:119], v[152:155], v[182:185], v[116:119]
	v_mfma_f32_16x16x32_bf16 v[100:103], v[152:155], v[190:193], v[100:103]
	v_mfma_f32_16x16x32_bf16 v[84:87], v[152:155], v[198:201], v[84:87]
	v_mfma_f32_16x16x32_bf16 v[68:71], v[152:155], v[206:209], v[68:71]
	v_mfma_f32_16x16x32_bf16 v[64:67], v[160:163], v[206:209], v[64:67]
	v_mfma_f32_16x16x32_bf16 v[80:83], v[160:163], v[198:201], v[80:83]
	v_mfma_f32_16x16x32_bf16 v[96:99], v[160:163], v[190:193], v[96:99]
	v_mfma_f32_16x16x32_bf16 v[112:115], v[160:163], v[182:185], v[112:115]
	v_mfma_f32_16x16x32_bf16 v[124:127], v[140:143], v[186:189], v[124:127]
	v_mfma_f32_16x16x32_bf16 v[108:111], v[140:143], v[194:197], v[108:111]
	v_mfma_f32_16x16x32_bf16 v[92:95], v[140:143], v[202:205], v[92:95]
	v_mfma_f32_16x16x32_bf16 v[76:79], v[140:143], v[220:223], v[76:79]
	v_mfma_f32_16x16x32_bf16 v[72:75], v[148:151], v[220:223], v[72:75]
	v_mfma_f32_16x16x32_bf16 v[88:91], v[148:151], v[202:205], v[88:91]
	v_mfma_f32_16x16x32_bf16 v[104:107], v[148:151], v[194:197], v[104:107]
	v_mfma_f32_16x16x32_bf16 v[120:123], v[148:151], v[186:189], v[120:123]
	v_mfma_f32_16x16x32_bf16 v[116:119], v[156:159], v[186:189], v[116:119]
	v_mfma_f32_16x16x32_bf16 v[100:103], v[156:159], v[194:197], v[100:103]
	v_mfma_f32_16x16x32_bf16 v[84:87], v[156:159], v[202:205], v[84:87]
	v_mfma_f32_16x16x32_bf16 v[68:71], v[156:159], v[220:223], v[68:71]
	v_mfma_f32_16x16x32_bf16 v[64:67], v[164:167], v[220:223], v[64:67]
	v_mfma_f32_16x16x32_bf16 v[80:83], v[164:167], v[202:205], v[80:83]
	v_mfma_f32_16x16x32_bf16 v[96:99], v[164:167], v[194:197], v[96:99]
	v_mfma_f32_16x16x32_bf16 v[112:115], v[164:167], v[186:189], v[112:115]
	s_barrier
	s_add_i32 s48, s48, s63
	v_lshl_add_u64 v[226:227], v[134:135], 0, s[10:11]
	s_mov_b32 m0, s48
	s_nop 0
	global_load_lds_dwordx4 v[226:227], off
	v_lshl_add_u64 v[226:227], v[134:135], 0, s[12:13]
	s_add_i32 m0, s48, 0x2000
	s_add_i32 s48, s49, s63
	global_load_lds_dwordx4 v[226:227], off
	v_lshl_add_u64 v[226:227], v[134:135], 0, s[14:15]
	s_mov_b32 m0, s48
	v_lshl_add_u64 v[134:135], v[134:135], 0, s[16:17]
	global_load_lds_dwordx4 v[226:227], off
	s_add_i32 m0, s48, 0x2000
	s_nop 0
	global_load_lds_dwordx4 v[134:135], off
	v_lshl_add_u64 v[134:135], v[224:225], 0, s[10:11]
	s_mov_b32 m0, s68
	s_nop 0
	global_load_lds_dwordx4 v[134:135], off
	v_lshl_add_u64 v[134:135], v[224:225], 0, s[12:13]
	s_mov_b32 m0, s69
	s_nop 0
	global_load_lds_dwordx4 v[134:135], off
	ds_read_b128 v[182:185], v138 offset:49152
	ds_read_b128 v[186:189], v138 offset:50176
	ds_read_b128 v[190:193], v138 offset:51200
	ds_read_b128 v[194:197], v138 offset:52224
	ds_read_b128 v[198:201], v138 offset:53248
	ds_read_b128 v[202:205], v138 offset:54272
	ds_read_b128 v[206:209], v138 offset:55296
	ds_read_b128 v[220:223], v138 offset:56320
	s_waitcnt vmcnt(8)
	s_waitcnt lgkmcnt(0)
	s_barrier
	s_waitcnt lgkmcnt(0)
	v_mfma_f32_16x16x32_bf16 v[60:63], v[130:133], v[182:185], v[60:63]
	v_mfma_f32_16x16x32_bf16 v[44:47], v[130:133], v[190:193], v[44:47]
	v_mfma_f32_16x16x32_bf16 v[28:31], v[130:133], v[198:201], v[28:31]
	v_mfma_f32_16x16x32_bf16 v[12:15], v[130:133], v[206:209], v[12:15]
	v_mfma_f32_16x16x32_bf16 v[8:11], v[144:147], v[206:209], v[8:11]
	v_mfma_f32_16x16x32_bf16 v[24:27], v[144:147], v[198:201], v[24:27]
	v_mfma_f32_16x16x32_bf16 v[40:43], v[144:147], v[190:193], v[40:43]
	v_mfma_f32_16x16x32_bf16 v[56:59], v[144:147], v[182:185], v[56:59]
	v_mfma_f32_16x16x32_bf16 v[52:55], v[152:155], v[182:185], v[52:55]
	v_mfma_f32_16x16x32_bf16 v[36:39], v[152:155], v[190:193], v[36:39]
	v_mfma_f32_16x16x32_bf16 v[20:23], v[152:155], v[198:201], v[20:23]
	v_mfma_f32_16x16x32_bf16 v[4:7], v[152:155], v[206:209], v[4:7]
	v_mfma_f32_16x16x32_bf16 v[0:3], v[160:163], v[206:209], v[0:3]
	v_mfma_f32_16x16x32_bf16 v[16:19], v[160:163], v[198:201], v[16:19]
	v_mfma_f32_16x16x32_bf16 v[32:35], v[160:163], v[190:193], v[32:35]
	v_mfma_f32_16x16x32_bf16 v[48:51], v[160:163], v[182:185], v[48:51]
	v_mfma_f32_16x16x32_bf16 v[60:63], v[140:143], v[186:189], v[60:63]
	v_mfma_f32_16x16x32_bf16 v[44:47], v[140:143], v[194:197], v[44:47]
	v_mfma_f32_16x16x32_bf16 v[28:31], v[140:143], v[202:205], v[28:31]
	v_mfma_f32_16x16x32_bf16 v[12:15], v[140:143], v[220:223], v[12:15]
	v_mfma_f32_16x16x32_bf16 v[8:11], v[148:151], v[220:223], v[8:11]
	v_mfma_f32_16x16x32_bf16 v[24:27], v[148:151], v[202:205], v[24:27]
	v_mfma_f32_16x16x32_bf16 v[40:43], v[148:151], v[194:197], v[40:43]
	v_mfma_f32_16x16x32_bf16 v[56:59], v[148:151], v[186:189], v[56:59]
	v_mfma_f32_16x16x32_bf16 v[52:55], v[156:159], v[186:189], v[52:55]
	v_mfma_f32_16x16x32_bf16 v[36:39], v[156:159], v[194:197], v[36:39]
	v_mfma_f32_16x16x32_bf16 v[20:23], v[156:159], v[202:205], v[20:23]
	v_mfma_f32_16x16x32_bf16 v[4:7], v[156:159], v[220:223], v[4:7]
	v_mfma_f32_16x16x32_bf16 v[0:3], v[164:167], v[220:223], v[0:3]
	v_mfma_f32_16x16x32_bf16 v[16:19], v[164:167], v[202:205], v[16:19]
	v_mfma_f32_16x16x32_bf16 v[32:35], v[164:167], v[194:197], v[32:35]
	v_mfma_f32_16x16x32_bf16 v[48:51], v[164:167], v[186:189], v[48:51]
	s_barrier
	s_cmp_gt_u32 s80, 13
	s_cbranch_scc0 .LBB0_784
	s_and_b64 vcc, exec, s[30:31]
	s_cbranch_vccz .LBB0_787
	s_barrier

.LBB0_856:
	s_add_i32 s78, s78, 2
	s_mov_b32 s50, s78
	s_ashr_i32 s51, s50, 31
	s_lshl_b64 s[80:81], s[50:51], 7
	v_lshl_add_u64 v[224:225], v[130:131], 0, s[80:81]
	v_lshl_add_u64 v[226:227], v[224:225], 0, s[10:11]
	s_add_i32 m0, s62, 0xc000
	s_nop 0
	global_load_lds_dwordx4 v[226:227], off
	v_lshl_add_u64 v[224:225], v[224:225], 0, s[12:13]
	s_add_i32 m0, s62, 0xe000
	s_nop 0
	global_load_lds_dwordx4 v[224:225], off
	s_add_u32 s51, s80, 0x100
	s_addc_u32 s79, s81, 0
	s_add_u32 s82, s30, s51
	s_addc_u32 s83, s31, s79
	s_add_u32 s84, s28, s51
	s_addc_u32 s79, s29, s79
	s_add_i32 s85, 0, 0x10000
	s_cmp_eq_u32 s50, 14
	s_cselect_b32 s51, s39, s83
	s_cselect_b32 s50, s76, s82
	v_add_u32_e32 v135, s85, v133
	s_cselect_b32 s83, s35, s79
	s_cselect_b32 s82, s77, s84
	s_add_i32 s79, 0, 0x14000
	ds_read_b128 v[136:139], v135
	ds_read_b128 v[140:143], v135 offset:1024
	ds_read_b128 v[144:147], v135 offset:2048
	ds_read_b128 v[148:151], v135 offset:3072
	v_add_u32_e32 v135, s79, v133
	ds_read_b128 v[152:155], v135
	ds_read_b128 v[156:159], v135 offset:1024
	ds_read_b128 v[160:163], v135 offset:2048
	ds_read_b128 v[164:167], v135 offset:3072
	ds_read_b128 v[182:185], v134
	ds_read_b128 v[186:189], v134 offset:1024
	ds_read_b128 v[190:193], v134 offset:2048
	ds_read_b128 v[194:197], v134 offset:3072
	ds_read_b128 v[198:201], v134 offset:4096
	ds_read_b128 v[202:205], v134 offset:5120
	ds_read_b128 v[206:209], v134 offset:6144
	ds_read_b128 v[220:223], v134 offset:7168
	s_nop 0
	s_waitcnt vmcnt(8)
	s_waitcnt lgkmcnt(0)
	s_barrier
	s_waitcnt lgkmcnt(0)
	v_mfma_f32_16x16x32_bf16 v[124:127], v[136:139], v[182:185], v[124:127]
	v_mfma_f32_16x16x32_bf16 v[116:119], v[136:139], v[190:193], v[116:119]
	v_mfma_f32_16x16x32_bf16 v[100:103], v[136:139], v[198:201], v[100:103]
	v_mfma_f32_16x16x32_bf16 v[84:87], v[136:139], v[206:209], v[84:87]
	v_mfma_f32_16x16x32_bf16 v[80:83], v[144:147], v[206:209], v[80:83]
	v_mfma_f32_16x16x32_bf16 v[96:99], v[144:147], v[198:201], v[96:99]
	v_mfma_f32_16x16x32_bf16 v[112:115], v[144:147], v[190:193], v[112:115]
	v_mfma_f32_16x16x32_bf16 v[120:123], v[144:147], v[182:185], v[120:123]
	v_mfma_f32_16x16x32_bf16 v[108:111], v[152:155], v[182:185], v[108:111]
	v_mfma_f32_16x16x32_bf16 v[92:95], v[152:155], v[190:193], v[92:95]
	v_mfma_f32_16x16x32_bf16 v[76:79], v[152:155], v[198:201], v[76:79]
	v_mfma_f32_16x16x32_bf16 v[68:71], v[152:155], v[206:209], v[68:71]
	v_mfma_f32_16x16x32_bf16 v[64:67], v[160:163], v[206:209], v[64:67]
	v_mfma_f32_16x16x32_bf16 v[72:75], v[160:163], v[198:201], v[72:75]
	v_mfma_f32_16x16x32_bf16 v[88:91], v[160:163], v[190:193], v[88:91]
	v_mfma_f32_16x16x32_bf16 v[104:107], v[160:163], v[182:185], v[104:107]
	v_mfma_f32_16x16x32_bf16 v[124:127], v[140:143], v[186:189], v[124:127]
	v_mfma_f32_16x16x32_bf16 v[116:119], v[140:143], v[194:197], v[116:119]
	v_mfma_f32_16x16x32_bf16 v[100:103], v[140:143], v[202:205], v[100:103]
	v_mfma_f32_16x16x32_bf16 v[84:87], v[140:143], v[220:223], v[84:87]
	v_mfma_f32_16x16x32_bf16 v[80:83], v[148:151], v[220:223], v[80:83]
	v_mfma_f32_16x16x32_bf16 v[96:99], v[148:151], v[202:205], v[96:99]
	v_mfma_f32_16x16x32_bf16 v[112:115], v[148:151], v[194:197], v[112:115]
	v_mfma_f32_16x16x32_bf16 v[120:123], v[148:151], v[186:189], v[120:123]
	v_mfma_f32_16x16x32_bf16 v[108:111], v[156:159], v[186:189], v[108:111]
	v_mfma_f32_16x16x32_bf16 v[92:95], v[156:159], v[194:197], v[92:95]
	v_mfma_f32_16x16x32_bf16 v[76:79], v[156:159], v[202:205], v[76:79]
	v_mfma_f32_16x16x32_bf16 v[68:71], v[156:159], v[220:223], v[68:71]
	v_mfma_f32_16x16x32_bf16 v[64:67], v[164:167], v[220:223], v[64:67]
	v_mfma_f32_16x16x32_bf16 v[72:75], v[164:167], v[202:205], v[72:75]
	v_mfma_f32_16x16x32_bf16 v[88:91], v[164:167], v[194:197], v[88:91]
	v_mfma_f32_16x16x32_bf16 v[104:107], v[164:167], v[186:189], v[104:107]
	s_barrier
	s_add_i32 s80, s85, s59
	v_lshl_add_u64 v[224:225], s[82:83], 0, v[172:173]
	s_mov_b32 m0, s80
	s_nop 0
	global_load_lds_dwordx4 v[224:225], off
	v_lshl_add_u64 v[226:227], v[224:225], 0, s[40:41]
	s_add_i32 m0, s80, 0x2000
	s_add_i32 s79, s79, s59
	global_load_lds_dwordx4 v[226:227], off
	v_lshl_add_u64 v[226:227], v[224:225], 0, s[4:5]
	s_mov_b32 m0, s79
	s_nop 0
	global_load_lds_dwordx4 v[226:227], off
	v_lshl_add_u64 v[226:227], v[224:225], 0, s[6:7]
	s_add_i32 m0, s79, 0x2000
	s_nop 0
	global_load_lds_dwordx4 v[226:227], off
	v_lshl_add_u64 v[226:227], s[50:51], 0, v[128:129]
	s_mov_b32 m0, s62
	v_lshl_add_u64 v[228:229], v[226:227], 0, s[40:41]
	global_load_lds_dwordx4 v[226:227], off
	s_mov_b32 m0, s63
	s_nop 0
	global_load_lds_dwordx4 v[228:229], off
	ds_read_b128 v[182:185], v134 offset:16384
	ds_read_b128 v[186:189], v134 offset:17408
	ds_read_b128 v[190:193], v134 offset:18432
	ds_read_b128 v[194:197], v134 offset:19456
	ds_read_b128 v[198:201], v134 offset:20480
	ds_read_b128 v[202:205], v134 offset:21504
	ds_read_b128 v[206:209], v134 offset:22528
	ds_read_b128 v[220:223], v134 offset:23552
	s_waitcnt vmcnt(8)
	s_waitcnt lgkmcnt(0)
	s_barrier
	s_waitcnt lgkmcnt(0)
	v_mfma_f32_16x16x32_bf16 v[60:63], v[136:139], v[182:185], v[60:63]
	v_mfma_f32_16x16x32_bf16 v[52:55], v[136:139], v[190:193], v[52:55]
	v_mfma_f32_16x16x32_bf16 v[36:39], v[136:139], v[198:201], v[36:39]
	v_mfma_f32_16x16x32_bf16 v[20:23], v[136:139], v[206:209], v[20:23]
	v_mfma_f32_16x16x32_bf16 v[16:19], v[144:147], v[206:209], v[16:19]
	v_mfma_f32_16x16x32_bf16 v[32:35], v[144:147], v[198:201], v[32:35]
	v_mfma_f32_16x16x32_bf16 v[48:51], v[144:147], v[190:193], v[48:51]
	v_mfma_f32_16x16x32_bf16 v[56:59], v[144:147], v[182:185], v[56:59]
	v_mfma_f32_16x16x32_bf16 v[44:47], v[152:155], v[182:185], v[44:47]
	v_mfma_f32_16x16x32_bf16 v[28:31], v[152:155], v[190:193], v[28:31]
	v_mfma_f32_16x16x32_bf16 v[12:15], v[152:155], v[198:201], v[12:15]
	v_mfma_f32_16x16x32_bf16 v[4:7], v[152:155], v[206:209], v[4:7]
	v_mfma_f32_16x16x32_bf16 v[0:3], v[160:163], v[206:209], v[0:3]
	v_mfma_f32_16x16x32_bf16 v[8:11], v[160:163], v[198:201], v[8:11]
	v_mfma_f32_16x16x32_bf16 v[24:27], v[160:163], v[190:193], v[24:27]
	v_mfma_f32_16x16x32_bf16 v[40:43], v[160:163], v[182:185], v[40:43]
	v_mfma_f32_16x16x32_bf16 v[60:63], v[140:143], v[186:189], v[60:63]
	v_mfma_f32_16x16x32_bf16 v[52:55], v[140:143], v[194:197], v[52:55]
	v_mfma_f32_16x16x32_bf16 v[36:39], v[140:143], v[202:205], v[36:39]
	v_mfma_f32_16x16x32_bf16 v[20:23], v[140:143], v[220:223], v[20:23]
	v_mfma_f32_16x16x32_bf16 v[16:19], v[148:151], v[220:223], v[16:19]
	v_mfma_f32_16x16x32_bf16 v[32:35], v[148:151], v[202:205], v[32:35]
	v_mfma_f32_16x16x32_bf16 v[48:51], v[148:151], v[194:197], v[48:51]
	v_mfma_f32_16x16x32_bf16 v[56:59], v[148:151], v[186:189], v[56:59]
	v_mfma_f32_16x16x32_bf16 v[44:47], v[156:159], v[186:189], v[44:47]
	v_mfma_f32_16x16x32_bf16 v[28:31], v[156:159], v[194:197], v[28:31]
	v_mfma_f32_16x16x32_bf16 v[12:15], v[156:159], v[202:205], v[12:15]
	v_mfma_f32_16x16x32_bf16 v[4:7], v[156:159], v[220:223], v[4:7]
	v_mfma_f32_16x16x32_bf16 v[0:3], v[164:167], v[220:223], v[0:3]
	v_mfma_f32_16x16x32_bf16 v[8:11], v[164:167], v[202:205], v[8:11]
	v_mfma_f32_16x16x32_bf16 v[24:27], v[164:167], v[194:197], v[24:27]
	v_mfma_f32_16x16x32_bf16 v[40:43], v[164:167], v[186:189], v[40:43]
	s_barrier
	s_mov_b32 m0, s68
	v_lshl_add_u64 v[228:229], v[226:227], 0, s[4:5]
	global_load_lds_dwordx4 v[228:229], off
	v_lshl_add_u64 v[228:229], v[226:227], 0, s[6:7]
	s_mov_b32 m0, s69
	s_nop 0
	global_load_lds_dwordx4 v[228:229], off
	s_add_i32 s50, 0, 0x18000
	v_add_u32_e32 v135, s50, v133
	s_add_i32 s51, 0, 0x1c000
	ds_read_b128 v[136:139], v135
	ds_read_b128 v[140:143], v135 offset:1024
	ds_read_b128 v[144:147], v135 offset:2048
	ds_read_b128 v[148:151], v135 offset:3072
	v_add_u32_e32 v135, s51, v133
	ds_read_b128 v[152:155], v135
	ds_read_b128 v[156:159], v135 offset:1024
	ds_read_b128 v[160:163], v135 offset:2048
	ds_read_b128 v[164:167], v135 offset:3072
	ds_read_b128 v[182:185], v134 offset:32768
	ds_read_b128 v[186:189], v134 offset:33792
	ds_read_b128 v[190:193], v134 offset:34816
	ds_read_b128 v[194:197], v134 offset:35840
	ds_read_b128 v[198:201], v134 offset:36864
	ds_read_b128 v[202:205], v134 offset:37888
	ds_read_b128 v[206:209], v134 offset:38912
	ds_read_b128 v[220:223], v134 offset:39936
	s_nop 0
	s_waitcnt vmcnt(8)
	s_waitcnt lgkmcnt(0)
	s_barrier
	s_waitcnt lgkmcnt(0)
	v_mfma_f32_16x16x32_bf16 v[124:127], v[136:139], v[182:185], v[124:127]
	v_mfma_f32_16x16x32_bf16 v[116:119], v[136:139], v[190:193], v[116:119]
	v_mfma_f32_16x16x32_bf16 v[100:103], v[136:139], v[198:201], v[100:103]
	v_mfma_f32_16x16x32_bf16 v[84:87], v[136:139], v[206:209], v[84:87]
	v_mfma_f32_16x16x32_bf16 v[80:83], v[144:147], v[206:209], v[80:83]
	v_mfma_f32_16x16x32_bf16 v[96:99], v[144:147], v[198:201], v[96:99]
	v_mfma_f32_16x16x32_bf16 v[112:115], v[144:147], v[190:193], v[112:115]
	v_mfma_f32_16x16x32_bf16 v[120:123], v[144:147], v[182:185], v[120:123]
	v_mfma_f32_16x16x32_bf16 v[108:111], v[152:155], v[182:185], v[108:111]
	v_mfma_f32_16x16x32_bf16 v[92:95], v[152:155], v[190:193], v[92:95]
	v_mfma_f32_16x16x32_bf16 v[76:79], v[152:155], v[198:201], v[76:79]
	v_mfma_f32_16x16x32_bf16 v[68:71], v[152:155], v[206:209], v[68:71]
	v_mfma_f32_16x16x32_bf16 v[64:67], v[160:163], v[206:209], v[64:67]
	v_mfma_f32_16x16x32_bf16 v[72:75], v[160:163], v[198:201], v[72:75]
	v_mfma_f32_16x16x32_bf16 v[88:91], v[160:163], v[190:193], v[88:91]
	v_mfma_f32_16x16x32_bf16 v[104:107], v[160:163], v[182:185], v[104:107]
	v_mfma_f32_16x16x32_bf16 v[124:127], v[140:143], v[186:189], v[124:127]
	v_mfma_f32_16x16x32_bf16 v[116:119], v[140:143], v[194:197], v[116:119]
	v_mfma_f32_16x16x32_bf16 v[100:103], v[140:143], v[202:205], v[100:103]
	v_mfma_f32_16x16x32_bf16 v[84:87], v[140:143], v[220:223], v[84:87]
	v_mfma_f32_16x16x32_bf16 v[80:83], v[148:151], v[220:223], v[80:83]
	v_mfma_f32_16x16x32_bf16 v[96:99], v[148:151], v[202:205], v[96:99]
	v_mfma_f32_16x16x32_bf16 v[112:115], v[148:151], v[194:197], v[112:115]
	v_mfma_f32_16x16x32_bf16 v[120:123], v[148:151], v[186:189], v[120:123]
	v_mfma_f32_16x16x32_bf16 v[108:111], v[156:159], v[186:189], v[108:111]
	v_mfma_f32_16x16x32_bf16 v[92:95], v[156:159], v[194:197], v[92:95]
	v_mfma_f32_16x16x32_bf16 v[76:79], v[156:159], v[202:205], v[76:79]
	v_mfma_f32_16x16x32_bf16 v[68:71], v[156:159], v[220:223], v[68:71]
	v_mfma_f32_16x16x32_bf16 v[64:67], v[164:167], v[220:223], v[64:67]
	v_mfma_f32_16x16x32_bf16 v[72:75], v[164:167], v[202:205], v[72:75]
	v_mfma_f32_16x16x32_bf16 v[88:91], v[164:167], v[194:197], v[88:91]
	v_mfma_f32_16x16x32_bf16 v[104:107], v[164:167], v[186:189], v[104:107]
	s_barrier
	s_add_i32 s50, s50, s59
	v_lshl_add_u64 v[228:229], v[224:225], 0, s[10:11]
	s_mov_b32 m0, s50
	s_nop 0
	global_load_lds_dwordx4 v[228:229], off
	v_lshl_add_u64 v[228:229], v[224:225], 0, s[12:13]
	s_add_i32 m0, s50, 0x2000
	s_add_i32 s50, s51, s59
	global_load_lds_dwordx4 v[228:229], off
	v_lshl_add_u64 v[228:229], v[224:225], 0, s[14:15]
	s_mov_b32 m0, s50
	v_lshl_add_u64 v[224:225], v[224:225], 0, s[16:17]
	global_load_lds_dwordx4 v[228:229], off
	s_add_i32 m0, s50, 0x2000
	s_nop 0
	global_load_lds_dwordx4 v[224:225], off
	v_lshl_add_u64 v[224:225], v[226:227], 0, s[10:11]
	s_mov_b32 m0, s72
	s_nop 0
	global_load_lds_dwordx4 v[224:225], off
	v_lshl_add_u64 v[224:225], v[226:227], 0, s[12:13]
	s_mov_b32 m0, s73
	s_nop 0
	global_load_lds_dwordx4 v[224:225], off
	ds_read_b128 v[182:185], v134 offset:49152
	ds_read_b128 v[186:189], v134 offset:50176
	ds_read_b128 v[190:193], v134 offset:51200
	ds_read_b128 v[194:197], v134 offset:52224
	ds_read_b128 v[198:201], v134 offset:53248
	ds_read_b128 v[202:205], v134 offset:54272
	ds_read_b128 v[206:209], v134 offset:55296
	ds_read_b128 v[220:223], v134 offset:56320
	s_waitcnt vmcnt(8)
	s_waitcnt lgkmcnt(0)
	s_barrier
	s_waitcnt lgkmcnt(0)
	v_mfma_f32_16x16x32_bf16 v[60:63], v[136:139], v[182:185], v[60:63]
	v_mfma_f32_16x16x32_bf16 v[52:55], v[136:139], v[190:193], v[52:55]
	v_mfma_f32_16x16x32_bf16 v[36:39], v[136:139], v[198:201], v[36:39]
	v_mfma_f32_16x16x32_bf16 v[20:23], v[136:139], v[206:209], v[20:23]
	v_mfma_f32_16x16x32_bf16 v[16:19], v[144:147], v[206:209], v[16:19]
	v_mfma_f32_16x16x32_bf16 v[32:35], v[144:147], v[198:201], v[32:35]
	v_mfma_f32_16x16x32_bf16 v[48:51], v[144:147], v[190:193], v[48:51]
	v_mfma_f32_16x16x32_bf16 v[56:59], v[144:147], v[182:185], v[56:59]
	v_mfma_f32_16x16x32_bf16 v[44:47], v[152:155], v[182:185], v[44:47]
	v_mfma_f32_16x16x32_bf16 v[28:31], v[152:155], v[190:193], v[28:31]
	v_mfma_f32_16x16x32_bf16 v[12:15], v[152:155], v[198:201], v[12:15]
	v_mfma_f32_16x16x32_bf16 v[4:7], v[152:155], v[206:209], v[4:7]
	v_mfma_f32_16x16x32_bf16 v[0:3], v[160:163], v[206:209], v[0:3]
	v_mfma_f32_16x16x32_bf16 v[8:11], v[160:163], v[198:201], v[8:11]
	v_mfma_f32_16x16x32_bf16 v[24:27], v[160:163], v[190:193], v[24:27]
	v_mfma_f32_16x16x32_bf16 v[40:43], v[160:163], v[182:185], v[40:43]
	v_mfma_f32_16x16x32_bf16 v[60:63], v[140:143], v[186:189], v[60:63]
	v_mfma_f32_16x16x32_bf16 v[52:55], v[140:143], v[194:197], v[52:55]
	v_mfma_f32_16x16x32_bf16 v[36:39], v[140:143], v[202:205], v[36:39]
	v_mfma_f32_16x16x32_bf16 v[20:23], v[140:143], v[220:223], v[20:23]
	v_mfma_f32_16x16x32_bf16 v[16:19], v[148:151], v[220:223], v[16:19]
	v_mfma_f32_16x16x32_bf16 v[32:35], v[148:151], v[202:205], v[32:35]
	v_mfma_f32_16x16x32_bf16 v[48:51], v[148:151], v[194:197], v[48:51]
	v_mfma_f32_16x16x32_bf16 v[56:59], v[148:151], v[186:189], v[56:59]
	v_mfma_f32_16x16x32_bf16 v[44:47], v[156:159], v[186:189], v[44:47]
	v_mfma_f32_16x16x32_bf16 v[28:31], v[156:159], v[194:197], v[28:31]
	v_mfma_f32_16x16x32_bf16 v[12:15], v[156:159], v[202:205], v[12:15]
	v_mfma_f32_16x16x32_bf16 v[4:7], v[156:159], v[220:223], v[4:7]
	v_mfma_f32_16x16x32_bf16 v[0:3], v[164:167], v[220:223], v[0:3]
	v_mfma_f32_16x16x32_bf16 v[8:11], v[164:167], v[202:205], v[8:11]
	v_mfma_f32_16x16x32_bf16 v[24:27], v[164:167], v[194:197], v[24:27]
	v_mfma_f32_16x16x32_bf16 v[40:43], v[164:167], v[186:189], v[40:43]
	s_barrier
	s_cmp_gt_u32 s78, 13
	s_cbranch_scc0 .LBB0_856
	s_and_b64 vcc, exec, s[8:9]
	s_cbranch_vccz .LBB0_859
	s_barrier

.LBB0_970:
	s_add_i32 s21, s21, 2
	s_mov_b32 s38, s21
	s_ashr_i32 s39, s38, 31
	s_lshl_b64 s[74:75], s[38:39], 7
	s_add_u32 s39, s74, 0x100
	s_addc_u32 s73, s75, 0
	s_add_u32 s76, s34, s39
	s_addc_u32 s77, s35, s73
	s_add_u32 s78, s30, s39
	s_addc_u32 s73, s31, s73
	s_cmp_eq_u32 s38, 14
	s_cselect_b32 s39, s67, s77
	s_cselect_b32 s38, s68, s76
	s_cselect_b32 s77, s23, s73
	s_cselect_b32 s76, s66, s78
	s_add_u32 s74, s34, s74
	s_addc_u32 s75, s35, s75
	v_lshl_add_u64 v[208:209], s[74:75], 0, v[130:131]
	s_mov_b32 m0, s59
	v_lshl_add_u64 v[216:217], v[208:209], 0, s[14:15]
	global_load_lds_dwordx4 v[216:217], off
	v_lshl_add_u64 v[208:209], v[208:209], 0, s[16:17]
	s_mov_b32 m0, s60
	s_nop 0
	global_load_lds_dwordx4 v[208:209], off
	ds_read_b128 v[144:147], v140
	ds_read_b128 v[148:151], v140 offset:1024
	ds_read_b128 v[152:155], v140 offset:2048
	ds_read_b128 v[156:159], v140 offset:3072
	ds_read_b128 v[160:163], v141
	ds_read_b128 v[164:167], v141 offset:1024
	ds_read_b128 v[172:175], v141 offset:2048
	ds_read_b128 v[176:179], v141 offset:3072
	ds_read_b128 v[180:183], v142
	ds_read_b128 v[184:187], v142 offset:1024
	ds_read_b128 v[188:191], v142 offset:2048
	ds_read_b128 v[192:195], v142 offset:3072
	ds_read_b128 v[196:199], v142 offset:4096
	ds_read_b128 v[200:203], v142 offset:5120
	ds_read_b128 v[204:207], v142 offset:6144
	ds_read_b128 v[212:215], v142 offset:7168
	s_waitcnt vmcnt(8)
	s_waitcnt lgkmcnt(0)
	s_barrier
	s_waitcnt lgkmcnt(0)
	v_mfma_f32_16x16x32_bf16 v[124:127], v[144:147], v[180:183], v[124:127]
	v_mfma_f32_16x16x32_bf16 v[108:111], v[144:147], v[188:191], v[108:111]
	v_mfma_f32_16x16x32_bf16 v[92:95], v[144:147], v[196:199], v[92:95]
	v_mfma_f32_16x16x32_bf16 v[76:79], v[144:147], v[204:207], v[76:79]
	v_mfma_f32_16x16x32_bf16 v[64:67], v[152:155], v[204:207], v[64:67]
	v_mfma_f32_16x16x32_bf16 v[80:83], v[152:155], v[196:199], v[80:83]
	v_mfma_f32_16x16x32_bf16 v[96:99], v[152:155], v[188:191], v[96:99]
	v_mfma_f32_16x16x32_bf16 v[112:115], v[152:155], v[180:183], v[112:115]
	v_mfma_f32_16x16x32_bf16 v[120:123], v[160:163], v[180:183], v[120:123]
	v_mfma_f32_16x16x32_bf16 v[104:107], v[160:163], v[188:191], v[104:107]
	v_mfma_f32_16x16x32_bf16 v[88:91], v[160:163], v[196:199], v[88:91]
	v_mfma_f32_16x16x32_bf16 v[72:75], v[160:163], v[204:207], v[72:75]
	v_mfma_f32_16x16x32_bf16 v[68:71], v[172:175], v[204:207], v[68:71]
	v_mfma_f32_16x16x32_bf16 v[84:87], v[172:175], v[196:199], v[84:87]
	v_mfma_f32_16x16x32_bf16 v[100:103], v[172:175], v[188:191], v[100:103]
	v_mfma_f32_16x16x32_bf16 v[116:119], v[172:175], v[180:183], v[116:119]
	v_mfma_f32_16x16x32_bf16 v[124:127], v[148:151], v[184:187], v[124:127]
	v_mfma_f32_16x16x32_bf16 v[108:111], v[148:151], v[192:195], v[108:111]
	v_mfma_f32_16x16x32_bf16 v[92:95], v[148:151], v[200:203], v[92:95]
	v_mfma_f32_16x16x32_bf16 v[76:79], v[148:151], v[212:215], v[76:79]
	v_mfma_f32_16x16x32_bf16 v[64:67], v[156:159], v[212:215], v[64:67]
	v_mfma_f32_16x16x32_bf16 v[80:83], v[156:159], v[200:203], v[80:83]
	v_mfma_f32_16x16x32_bf16 v[96:99], v[156:159], v[192:195], v[96:99]
	v_mfma_f32_16x16x32_bf16 v[112:115], v[156:159], v[184:187], v[112:115]
	v_mfma_f32_16x16x32_bf16 v[120:123], v[164:167], v[184:187], v[120:123]
	v_mfma_f32_16x16x32_bf16 v[104:107], v[164:167], v[192:195], v[104:107]
	v_mfma_f32_16x16x32_bf16 v[88:91], v[164:167], v[200:203], v[88:91]
	v_mfma_f32_16x16x32_bf16 v[72:75], v[164:167], v[212:215], v[72:75]
	v_mfma_f32_16x16x32_bf16 v[68:71], v[176:179], v[212:215], v[68:71]
	v_mfma_f32_16x16x32_bf16 v[84:87], v[176:179], v[200:203], v[84:87]
	v_mfma_f32_16x16x32_bf16 v[100:103], v[176:179], v[192:195], v[100:103]
	v_mfma_f32_16x16x32_bf16 v[116:119], v[176:179], v[184:187], v[116:119]
	s_barrier
	s_mov_b32 m0, s61
	v_lshl_add_u64 v[208:209], s[76:77], 0, v[128:129]
	global_load_lds_dwordx4 v[208:209], off
	v_lshl_add_u64 v[216:217], v[208:209], 0, s[0:1]
	s_mov_b32 m0, s62
	s_nop 0
	global_load_lds_dwordx4 v[216:217], off
	v_lshl_add_u64 v[216:217], v[208:209], 0, s[2:3]
	s_mov_b32 m0, s63
	s_nop 0
	global_load_lds_dwordx4 v[216:217], off
	v_lshl_add_u64 v[216:217], v[208:209], 0, s[4:5]
	s_mov_b32 m0, s64
	s_nop 0
	global_load_lds_dwordx4 v[216:217], off
	v_lshl_add_u64 v[216:217], s[38:39], 0, v[130:131]
	s_mov_b32 m0, s48
	v_lshl_add_u64 v[218:219], v[216:217], 0, s[0:1]
	global_load_lds_dwordx4 v[216:217], off
	s_mov_b32 m0, s49
	s_nop 0
	global_load_lds_dwordx4 v[218:219], off
	ds_read_b128 v[180:183], v142 offset:16384
	ds_read_b128 v[184:187], v142 offset:17408
	ds_read_b128 v[188:191], v142 offset:18432
	ds_read_b128 v[192:195], v142 offset:19456
	ds_read_b128 v[196:199], v142 offset:20480
	ds_read_b128 v[200:203], v142 offset:21504
	ds_read_b128 v[204:207], v142 offset:22528
	ds_read_b128 v[212:215], v142 offset:23552
	s_waitcnt vmcnt(8)
	s_waitcnt lgkmcnt(0)
	s_barrier
	s_waitcnt lgkmcnt(0)
	v_mfma_f32_16x16x32_bf16 v[60:63], v[144:147], v[180:183], v[60:63]
	v_mfma_f32_16x16x32_bf16 v[44:47], v[144:147], v[188:191], v[44:47]
	v_mfma_f32_16x16x32_bf16 v[28:31], v[144:147], v[196:199], v[28:31]
	v_mfma_f32_16x16x32_bf16 v[12:15], v[144:147], v[204:207], v[12:15]
	v_mfma_f32_16x16x32_bf16 v[0:3], v[152:155], v[204:207], v[0:3]
	v_mfma_f32_16x16x32_bf16 v[16:19], v[152:155], v[196:199], v[16:19]
	v_mfma_f32_16x16x32_bf16 v[32:35], v[152:155], v[188:191], v[32:35]
	v_mfma_f32_16x16x32_bf16 v[48:51], v[152:155], v[180:183], v[48:51]
	v_mfma_f32_16x16x32_bf16 v[56:59], v[160:163], v[180:183], v[56:59]
	v_mfma_f32_16x16x32_bf16 v[40:43], v[160:163], v[188:191], v[40:43]
	v_mfma_f32_16x16x32_bf16 v[24:27], v[160:163], v[196:199], v[24:27]
	v_mfma_f32_16x16x32_bf16 v[8:11], v[160:163], v[204:207], v[8:11]
	v_mfma_f32_16x16x32_bf16 v[4:7], v[172:175], v[204:207], v[4:7]
	v_mfma_f32_16x16x32_bf16 v[20:23], v[172:175], v[196:199], v[20:23]
	v_mfma_f32_16x16x32_bf16 v[36:39], v[172:175], v[188:191], v[36:39]
	v_mfma_f32_16x16x32_bf16 v[52:55], v[172:175], v[180:183], v[52:55]
	v_mfma_f32_16x16x32_bf16 v[60:63], v[148:151], v[184:187], v[60:63]
	v_mfma_f32_16x16x32_bf16 v[44:47], v[148:151], v[192:195], v[44:47]
	v_mfma_f32_16x16x32_bf16 v[28:31], v[148:151], v[200:203], v[28:31]
	v_mfma_f32_16x16x32_bf16 v[12:15], v[148:151], v[212:215], v[12:15]
	v_mfma_f32_16x16x32_bf16 v[0:3], v[156:159], v[212:215], v[0:3]
	v_mfma_f32_16x16x32_bf16 v[16:19], v[156:159], v[200:203], v[16:19]
	v_mfma_f32_16x16x32_bf16 v[32:35], v[156:159], v[192:195], v[32:35]
	v_mfma_f32_16x16x32_bf16 v[48:51], v[156:159], v[184:187], v[48:51]
	v_mfma_f32_16x16x32_bf16 v[56:59], v[164:167], v[184:187], v[56:59]
	v_mfma_f32_16x16x32_bf16 v[40:43], v[164:167], v[192:195], v[40:43]
	v_mfma_f32_16x16x32_bf16 v[24:27], v[164:167], v[200:203], v[24:27]
	v_mfma_f32_16x16x32_bf16 v[8:11], v[164:167], v[212:215], v[8:11]
	v_mfma_f32_16x16x32_bf16 v[4:7], v[176:179], v[212:215], v[4:7]
	v_mfma_f32_16x16x32_bf16 v[20:23], v[176:179], v[200:203], v[20:23]
	v_mfma_f32_16x16x32_bf16 v[36:39], v[176:179], v[192:195], v[36:39]
	v_mfma_f32_16x16x32_bf16 v[52:55], v[176:179], v[184:187], v[52:55]
	s_barrier
	s_mov_b32 m0, s50
	v_lshl_add_u64 v[218:219], v[216:217], 0, s[2:3]
	global_load_lds_dwordx4 v[218:219], off
	v_lshl_add_u64 v[218:219], v[216:217], 0, s[4:5]
	s_mov_b32 m0, s51
	s_nop 0
	global_load_lds_dwordx4 v[218:219], off
	ds_read_b128 v[144:147], v143
	ds_read_b128 v[148:151], v143 offset:1024
	ds_read_b128 v[152:155], v143 offset:2048
	ds_read_b128 v[156:159], v143 offset:3072
	ds_read_b128 v[160:163], v136
	ds_read_b128 v[164:167], v136 offset:1024
	ds_read_b128 v[172:175], v136 offset:2048
	ds_read_b128 v[176:179], v136 offset:3072
	ds_read_b128 v[180:183], v142 offset:32768
	ds_read_b128 v[184:187], v142 offset:33792
	ds_read_b128 v[188:191], v142 offset:34816
	ds_read_b128 v[192:195], v142 offset:35840
	ds_read_b128 v[196:199], v142 offset:36864
	ds_read_b128 v[200:203], v142 offset:37888
	ds_read_b128 v[204:207], v142 offset:38912
	ds_read_b128 v[212:215], v142 offset:39936
	s_waitcnt vmcnt(8)
	s_waitcnt lgkmcnt(0)
	s_barrier
	s_waitcnt lgkmcnt(0)
	v_mfma_f32_16x16x32_bf16 v[124:127], v[144:147], v[180:183], v[124:127]
	v_mfma_f32_16x16x32_bf16 v[108:111], v[144:147], v[188:191], v[108:111]
	v_mfma_f32_16x16x32_bf16 v[92:95], v[144:147], v[196:199], v[92:95]
	v_mfma_f32_16x16x32_bf16 v[76:79], v[144:147], v[204:207], v[76:79]
	v_mfma_f32_16x16x32_bf16 v[64:67], v[152:155], v[204:207], v[64:67]
	v_mfma_f32_16x16x32_bf16 v[80:83], v[152:155], v[196:199], v[80:83]
	v_mfma_f32_16x16x32_bf16 v[96:99], v[152:155], v[188:191], v[96:99]
	v_mfma_f32_16x16x32_bf16 v[112:115], v[152:155], v[180:183], v[112:115]
	v_mfma_f32_16x16x32_bf16 v[120:123], v[160:163], v[180:183], v[120:123]
	v_mfma_f32_16x16x32_bf16 v[104:107], v[160:163], v[188:191], v[104:107]
	v_mfma_f32_16x16x32_bf16 v[88:91], v[160:163], v[196:199], v[88:91]
	v_mfma_f32_16x16x32_bf16 v[72:75], v[160:163], v[204:207], v[72:75]
	v_mfma_f32_16x16x32_bf16 v[68:71], v[172:175], v[204:207], v[68:71]
	v_mfma_f32_16x16x32_bf16 v[84:87], v[172:175], v[196:199], v[84:87]
	v_mfma_f32_16x16x32_bf16 v[100:103], v[172:175], v[188:191], v[100:103]
	v_mfma_f32_16x16x32_bf16 v[116:119], v[172:175], v[180:183], v[116:119]
	v_mfma_f32_16x16x32_bf16 v[124:127], v[148:151], v[184:187], v[124:127]
	v_mfma_f32_16x16x32_bf16 v[108:111], v[148:151], v[192:195], v[108:111]
	v_mfma_f32_16x16x32_bf16 v[92:95], v[148:151], v[200:203], v[92:95]
	v_mfma_f32_16x16x32_bf16 v[76:79], v[148:151], v[212:215], v[76:79]
	v_mfma_f32_16x16x32_bf16 v[64:67], v[156:159], v[212:215], v[64:67]
	v_mfma_f32_16x16x32_bf16 v[80:83], v[156:159], v[200:203], v[80:83]
	v_mfma_f32_16x16x32_bf16 v[96:99], v[156:159], v[192:195], v[96:99]
	v_mfma_f32_16x16x32_bf16 v[112:115], v[156:159], v[184:187], v[112:115]
	v_mfma_f32_16x16x32_bf16 v[120:123], v[164:167], v[184:187], v[120:123]
	v_mfma_f32_16x16x32_bf16 v[104:107], v[164:167], v[192:195], v[104:107]
	v_mfma_f32_16x16x32_bf16 v[88:91], v[164:167], v[200:203], v[88:91]
	v_mfma_f32_16x16x32_bf16 v[72:75], v[164:167], v[212:215], v[72:75]
	v_mfma_f32_16x16x32_bf16 v[68:71], v[176:179], v[212:215], v[68:71]
	v_mfma_f32_16x16x32_bf16 v[84:87], v[176:179], v[200:203], v[84:87]
	v_mfma_f32_16x16x32_bf16 v[100:103], v[176:179], v[192:195], v[100:103]
	v_mfma_f32_16x16x32_bf16 v[116:119], v[176:179], v[184:187], v[116:119]
	s_barrier
	s_mov_b32 m0, s69
	v_lshl_add_u64 v[218:219], v[208:209], 0, s[10:11]
	global_load_lds_dwordx4 v[218:219], off
	v_lshl_add_u64 v[218:219], v[208:209], 0, s[12:13]
	s_mov_b32 m0, s70
	s_nop 0
	global_load_lds_dwordx4 v[218:219], off
	v_lshl_add_u64 v[218:219], v[208:209], 0, s[14:15]
	s_mov_b32 m0, s71
	v_lshl_add_u64 v[208:209], v[208:209], 0, s[16:17]
	global_load_lds_dwordx4 v[218:219], off
	s_mov_b32 m0, s72
	s_nop 0
	global_load_lds_dwordx4 v[208:209], off
	v_lshl_add_u64 v[208:209], v[216:217], 0, s[10:11]
	s_mov_b32 m0, s53
	s_nop 0
	global_load_lds_dwordx4 v[208:209], off
	v_lshl_add_u64 v[208:209], v[216:217], 0, s[12:13]
	s_mov_b32 m0, s54
	s_nop 0
	global_load_lds_dwordx4 v[208:209], off
	ds_read_b128 v[180:183], v142 offset:49152
	ds_read_b128 v[184:187], v142 offset:50176
	ds_read_b128 v[188:191], v142 offset:51200
	ds_read_b128 v[192:195], v142 offset:52224
	ds_read_b128 v[196:199], v142 offset:53248
	ds_read_b128 v[200:203], v142 offset:54272
	ds_read_b128 v[204:207], v142 offset:55296
	ds_read_b128 v[212:215], v142 offset:56320
	s_waitcnt vmcnt(8)
	s_waitcnt lgkmcnt(0)
	s_barrier
	s_waitcnt lgkmcnt(0)
	v_mfma_f32_16x16x32_bf16 v[60:63], v[144:147], v[180:183], v[60:63]
	v_mfma_f32_16x16x32_bf16 v[44:47], v[144:147], v[188:191], v[44:47]
	v_mfma_f32_16x16x32_bf16 v[28:31], v[144:147], v[196:199], v[28:31]
	v_mfma_f32_16x16x32_bf16 v[12:15], v[144:147], v[204:207], v[12:15]
	v_mfma_f32_16x16x32_bf16 v[0:3], v[152:155], v[204:207], v[0:3]
	v_mfma_f32_16x16x32_bf16 v[16:19], v[152:155], v[196:199], v[16:19]
	v_mfma_f32_16x16x32_bf16 v[32:35], v[152:155], v[188:191], v[32:35]
	v_mfma_f32_16x16x32_bf16 v[48:51], v[152:155], v[180:183], v[48:51]
	v_mfma_f32_16x16x32_bf16 v[56:59], v[160:163], v[180:183], v[56:59]
	v_mfma_f32_16x16x32_bf16 v[40:43], v[160:163], v[188:191], v[40:43]
	v_mfma_f32_16x16x32_bf16 v[24:27], v[160:163], v[196:199], v[24:27]
	v_mfma_f32_16x16x32_bf16 v[8:11], v[160:163], v[204:207], v[8:11]
	v_mfma_f32_16x16x32_bf16 v[4:7], v[172:175], v[204:207], v[4:7]
	v_mfma_f32_16x16x32_bf16 v[20:23], v[172:175], v[196:199], v[20:23]
	v_mfma_f32_16x16x32_bf16 v[36:39], v[172:175], v[188:191], v[36:39]
	v_mfma_f32_16x16x32_bf16 v[52:55], v[172:175], v[180:183], v[52:55]
	v_mfma_f32_16x16x32_bf16 v[60:63], v[148:151], v[184:187], v[60:63]
	v_mfma_f32_16x16x32_bf16 v[44:47], v[148:151], v[192:195], v[44:47]
	v_mfma_f32_16x16x32_bf16 v[28:31], v[148:151], v[200:203], v[28:31]
	v_mfma_f32_16x16x32_bf16 v[12:15], v[148:151], v[212:215], v[12:15]
	v_mfma_f32_16x16x32_bf16 v[0:3], v[156:159], v[212:215], v[0:3]
	v_mfma_f32_16x16x32_bf16 v[16:19], v[156:159], v[200:203], v[16:19]
	v_mfma_f32_16x16x32_bf16 v[32:35], v[156:159], v[192:195], v[32:35]
	v_mfma_f32_16x16x32_bf16 v[48:51], v[156:159], v[184:187], v[48:51]
	v_mfma_f32_16x16x32_bf16 v[56:59], v[164:167], v[184:187], v[56:59]
	v_mfma_f32_16x16x32_bf16 v[40:43], v[164:167], v[192:195], v[40:43]
	v_mfma_f32_16x16x32_bf16 v[24:27], v[164:167], v[200:203], v[24:27]
	v_mfma_f32_16x16x32_bf16 v[8:11], v[164:167], v[212:215], v[8:11]
	v_mfma_f32_16x16x32_bf16 v[4:7], v[176:179], v[212:215], v[4:7]
	v_mfma_f32_16x16x32_bf16 v[20:23], v[176:179], v[200:203], v[20:23]
	v_mfma_f32_16x16x32_bf16 v[36:39], v[176:179], v[192:195], v[36:39]
	v_mfma_f32_16x16x32_bf16 v[52:55], v[176:179], v[184:187], v[52:55]
	s_barrier
	s_cmp_gt_u32 s21, 13
	s_cbranch_scc0 .LBB0_970
	s_and_b64 vcc, exec, s[18:19]
	s_cbranch_vccz .LBB0_973
	s_barrier

.LBB0_1046:
	s_add_i32 s55, s55, 2
	s_mov_b32 s56, s55
	s_ashr_i32 s57, s56, 31
	s_lshl_b64 s[58:59], s[56:57], 7
	s_add_u32 s57, s58, 0x100
	s_addc_u32 s60, s59, 0
	s_add_u32 s61, s24, s57
	s_addc_u32 s62, s25, s60
	s_add_u32 s63, s22, s57
	s_addc_u32 s60, s23, s60
	s_cmp_eq_u32 s56, 42
	s_cselect_b32 s57, s1, s62
	s_cselect_b32 s56, s0, s61
	s_cselect_b32 s61, s27, s60
	s_cselect_b32 s60, s26, s63
	v_lshl_add_u64 v[208:209], v[136:137], 0, s[58:59]
	v_lshl_add_u64 v[216:217], v[208:209], 0, s[12:13]
	s_add_i32 m0, s39, 0xc000
	s_nop 0
	global_load_lds_dwordx4 v[216:217], off
	v_lshl_add_u64 v[208:209], v[208:209], 0, s[14:15]
	s_add_i32 m0, s39, 0xe000
	s_nop 0
	global_load_lds_dwordx4 v[208:209], off
	ds_read_b128 v[144:147], v140
	ds_read_b128 v[148:151], v140 offset:1024
	ds_read_b128 v[152:155], v140 offset:2048
	ds_read_b128 v[156:159], v140 offset:3072
	ds_read_b128 v[160:163], v141
	ds_read_b128 v[164:167], v141 offset:1024
	ds_read_b128 v[172:175], v141 offset:2048
	ds_read_b128 v[176:179], v141 offset:3072
	ds_read_b128 v[180:183], v142
	ds_read_b128 v[184:187], v142 offset:1024
	ds_read_b128 v[188:191], v142 offset:2048
	ds_read_b128 v[192:195], v142 offset:3072
	ds_read_b128 v[196:199], v142 offset:4096
	ds_read_b128 v[200:203], v142 offset:5120
	ds_read_b128 v[204:207], v142 offset:6144
	ds_read_b128 v[212:215], v142 offset:7168
	s_waitcnt vmcnt(8)
	s_waitcnt lgkmcnt(0)
	s_barrier
	s_waitcnt lgkmcnt(0)
	v_mfma_f32_16x16x32_bf16 v[124:127], v[144:147], v[180:183], v[124:127]
	v_mfma_f32_16x16x32_bf16 v[116:119], v[144:147], v[188:191], v[116:119]
	v_mfma_f32_16x16x32_bf16 v[100:103], v[144:147], v[196:199], v[100:103]
	v_mfma_f32_16x16x32_bf16 v[84:87], v[144:147], v[204:207], v[84:87]
	v_mfma_f32_16x16x32_bf16 v[80:83], v[152:155], v[204:207], v[80:83]
	v_mfma_f32_16x16x32_bf16 v[96:99], v[152:155], v[196:199], v[96:99]
	v_mfma_f32_16x16x32_bf16 v[112:115], v[152:155], v[188:191], v[112:115]
	v_mfma_f32_16x16x32_bf16 v[120:123], v[152:155], v[180:183], v[120:123]
	v_mfma_f32_16x16x32_bf16 v[108:111], v[160:163], v[180:183], v[108:111]
	v_mfma_f32_16x16x32_bf16 v[92:95], v[160:163], v[188:191], v[92:95]
	v_mfma_f32_16x16x32_bf16 v[76:79], v[160:163], v[196:199], v[76:79]
	v_mfma_f32_16x16x32_bf16 v[68:71], v[160:163], v[204:207], v[68:71]
	v_mfma_f32_16x16x32_bf16 v[64:67], v[172:175], v[204:207], v[64:67]
	v_mfma_f32_16x16x32_bf16 v[72:75], v[172:175], v[196:199], v[72:75]
	v_mfma_f32_16x16x32_bf16 v[88:91], v[172:175], v[188:191], v[88:91]
	v_mfma_f32_16x16x32_bf16 v[104:107], v[172:175], v[180:183], v[104:107]
	v_mfma_f32_16x16x32_bf16 v[124:127], v[148:151], v[184:187], v[124:127]
	v_mfma_f32_16x16x32_bf16 v[116:119], v[148:151], v[192:195], v[116:119]
	v_mfma_f32_16x16x32_bf16 v[100:103], v[148:151], v[200:203], v[100:103]
	v_mfma_f32_16x16x32_bf16 v[84:87], v[148:151], v[212:215], v[84:87]
	v_mfma_f32_16x16x32_bf16 v[80:83], v[156:159], v[212:215], v[80:83]
	v_mfma_f32_16x16x32_bf16 v[96:99], v[156:159], v[200:203], v[96:99]
	v_mfma_f32_16x16x32_bf16 v[112:115], v[156:159], v[192:195], v[112:115]
	v_mfma_f32_16x16x32_bf16 v[120:123], v[156:159], v[184:187], v[120:123]
	v_mfma_f32_16x16x32_bf16 v[108:111], v[164:167], v[184:187], v[108:111]
	v_mfma_f32_16x16x32_bf16 v[92:95], v[164:167], v[192:195], v[92:95]
	v_mfma_f32_16x16x32_bf16 v[76:79], v[164:167], v[200:203], v[76:79]
	v_mfma_f32_16x16x32_bf16 v[68:71], v[164:167], v[212:215], v[68:71]
	v_mfma_f32_16x16x32_bf16 v[64:67], v[176:179], v[212:215], v[64:67]
	v_mfma_f32_16x16x32_bf16 v[72:75], v[176:179], v[200:203], v[72:75]
	v_mfma_f32_16x16x32_bf16 v[88:91], v[176:179], v[192:195], v[88:91]
	v_mfma_f32_16x16x32_bf16 v[104:107], v[176:179], v[184:187], v[104:107]
	s_barrier
	s_add_i32 s58, s49, s38
	v_lshl_add_u64 v[208:209], s[60:61], 0, v[130:131]
	s_mov_b32 m0, s58
	s_nop 0
	global_load_lds_dwordx4 v[208:209], off
	v_lshl_add_u64 v[216:217], v[208:209], 0, s[2:3]
	s_add_i32 m0, s58, 0x2000
	s_add_i32 s58, s50, s38
	global_load_lds_dwordx4 v[216:217], off
	v_lshl_add_u64 v[216:217], v[208:209], 0, s[4:5]
	s_mov_b32 m0, s58
	s_nop 0
	global_load_lds_dwordx4 v[216:217], off
	v_lshl_add_u64 v[216:217], v[208:209], 0, s[6:7]
	s_add_i32 m0, s58, 0x2000
	s_nop 0
	global_load_lds_dwordx4 v[216:217], off
	v_lshl_add_u64 v[216:217], s[56:57], 0, v[128:129]
	s_mov_b32 m0, s39
	v_lshl_add_u64 v[218:219], v[216:217], 0, s[2:3]
	global_load_lds_dwordx4 v[216:217], off
	s_mov_b32 m0, s40
	s_nop 0
	global_load_lds_dwordx4 v[218:219], off
	ds_read_b128 v[180:183], v142 offset:16384
	ds_read_b128 v[184:187], v142 offset:17408
	ds_read_b128 v[188:191], v142 offset:18432
	ds_read_b128 v[192:195], v142 offset:19456
	ds_read_b128 v[196:199], v142 offset:20480
	ds_read_b128 v[200:203], v142 offset:21504
	ds_read_b128 v[204:207], v142 offset:22528
	ds_read_b128 v[212:215], v142 offset:23552
	s_waitcnt vmcnt(8)
	s_waitcnt lgkmcnt(0)
	s_barrier
	s_waitcnt lgkmcnt(0)
	v_mfma_f32_16x16x32_bf16 v[60:63], v[144:147], v[180:183], v[60:63]
	v_mfma_f32_16x16x32_bf16 v[52:55], v[144:147], v[188:191], v[52:55]
	v_mfma_f32_16x16x32_bf16 v[36:39], v[144:147], v[196:199], v[36:39]
	v_mfma_f32_16x16x32_bf16 v[20:23], v[144:147], v[204:207], v[20:23]
	v_mfma_f32_16x16x32_bf16 v[16:19], v[152:155], v[204:207], v[16:19]
	v_mfma_f32_16x16x32_bf16 v[32:35], v[152:155], v[196:199], v[32:35]
	v_mfma_f32_16x16x32_bf16 v[48:51], v[152:155], v[188:191], v[48:51]
	v_mfma_f32_16x16x32_bf16 v[56:59], v[152:155], v[180:183], v[56:59]
	v_mfma_f32_16x16x32_bf16 v[44:47], v[160:163], v[180:183], v[44:47]
	v_mfma_f32_16x16x32_bf16 v[28:31], v[160:163], v[188:191], v[28:31]
	v_mfma_f32_16x16x32_bf16 v[12:15], v[160:163], v[196:199], v[12:15]
	v_mfma_f32_16x16x32_bf16 v[4:7], v[160:163], v[204:207], v[4:7]
	v_mfma_f32_16x16x32_bf16 v[0:3], v[172:175], v[204:207], v[0:3]
	v_mfma_f32_16x16x32_bf16 v[8:11], v[172:175], v[196:199], v[8:11]
	v_mfma_f32_16x16x32_bf16 v[24:27], v[172:175], v[188:191], v[24:27]
	v_mfma_f32_16x16x32_bf16 v[40:43], v[172:175], v[180:183], v[40:43]
	v_mfma_f32_16x16x32_bf16 v[60:63], v[148:151], v[184:187], v[60:63]
	v_mfma_f32_16x16x32_bf16 v[52:55], v[148:151], v[192:195], v[52:55]
	v_mfma_f32_16x16x32_bf16 v[36:39], v[148:151], v[200:203], v[36:39]
	v_mfma_f32_16x16x32_bf16 v[20:23], v[148:151], v[212:215], v[20:23]
	v_mfma_f32_16x16x32_bf16 v[16:19], v[156:159], v[212:215], v[16:19]
	v_mfma_f32_16x16x32_bf16 v[32:35], v[156:159], v[200:203], v[32:35]
	v_mfma_f32_16x16x32_bf16 v[48:51], v[156:159], v[192:195], v[48:51]
	v_mfma_f32_16x16x32_bf16 v[56:59], v[156:159], v[184:187], v[56:59]
	v_mfma_f32_16x16x32_bf16 v[44:47], v[164:167], v[184:187], v[44:47]
	v_mfma_f32_16x16x32_bf16 v[28:31], v[164:167], v[192:195], v[28:31]
	v_mfma_f32_16x16x32_bf16 v[12:15], v[164:167], v[200:203], v[12:15]
	v_mfma_f32_16x16x32_bf16 v[4:7], v[164:167], v[212:215], v[4:7]
	v_mfma_f32_16x16x32_bf16 v[0:3], v[176:179], v[212:215], v[0:3]
	v_mfma_f32_16x16x32_bf16 v[8:11], v[176:179], v[200:203], v[8:11]
	v_mfma_f32_16x16x32_bf16 v[24:27], v[176:179], v[192:195], v[24:27]
	v_mfma_f32_16x16x32_bf16 v[40:43], v[176:179], v[184:187], v[40:43]
	s_barrier
	s_mov_b32 m0, s41
	v_lshl_add_u64 v[218:219], v[216:217], 0, s[4:5]
	global_load_lds_dwordx4 v[218:219], off
	v_lshl_add_u64 v[218:219], v[216:217], 0, s[6:7]
	s_mov_b32 m0, s42
	s_nop 0
	global_load_lds_dwordx4 v[218:219], off
	s_add_i32 s56, 0, 0x18000
	v_add_u32_e32 v143, s56, v139
	s_add_i32 s57, 0, 0x1c000
	ds_read_b128 v[144:147], v143
	ds_read_b128 v[148:151], v143 offset:1024
	ds_read_b128 v[152:155], v143 offset:2048
	ds_read_b128 v[156:159], v143 offset:3072
	v_add_u32_e32 v143, s57, v139
	ds_read_b128 v[160:163], v143
	ds_read_b128 v[164:167], v143 offset:1024
	ds_read_b128 v[172:175], v143 offset:2048
	ds_read_b128 v[176:179], v143 offset:3072
	ds_read_b128 v[180:183], v142 offset:32768
	ds_read_b128 v[184:187], v142 offset:33792
	ds_read_b128 v[188:191], v142 offset:34816
	ds_read_b128 v[192:195], v142 offset:35840
	ds_read_b128 v[196:199], v142 offset:36864
	ds_read_b128 v[200:203], v142 offset:37888
	ds_read_b128 v[204:207], v142 offset:38912
	ds_read_b128 v[212:215], v142 offset:39936
	s_nop 0
	s_waitcnt vmcnt(8)
	s_waitcnt lgkmcnt(0)
	s_barrier
	s_waitcnt lgkmcnt(0)
	v_mfma_f32_16x16x32_bf16 v[124:127], v[144:147], v[180:183], v[124:127]
	v_mfma_f32_16x16x32_bf16 v[116:119], v[144:147], v[188:191], v[116:119]
	v_mfma_f32_16x16x32_bf16 v[100:103], v[144:147], v[196:199], v[100:103]
	v_mfma_f32_16x16x32_bf16 v[84:87], v[144:147], v[204:207], v[84:87]
	v_mfma_f32_16x16x32_bf16 v[80:83], v[152:155], v[204:207], v[80:83]
	v_mfma_f32_16x16x32_bf16 v[96:99], v[152:155], v[196:199], v[96:99]
	v_mfma_f32_16x16x32_bf16 v[112:115], v[152:155], v[188:191], v[112:115]
	v_mfma_f32_16x16x32_bf16 v[120:123], v[152:155], v[180:183], v[120:123]
	v_mfma_f32_16x16x32_bf16 v[108:111], v[160:163], v[180:183], v[108:111]
	v_mfma_f32_16x16x32_bf16 v[92:95], v[160:163], v[188:191], v[92:95]
	v_mfma_f32_16x16x32_bf16 v[76:79], v[160:163], v[196:199], v[76:79]
	v_mfma_f32_16x16x32_bf16 v[68:71], v[160:163], v[204:207], v[68:71]
	v_mfma_f32_16x16x32_bf16 v[64:67], v[172:175], v[204:207], v[64:67]
	v_mfma_f32_16x16x32_bf16 v[72:75], v[172:175], v[196:199], v[72:75]
	v_mfma_f32_16x16x32_bf16 v[88:91], v[172:175], v[188:191], v[88:91]
	v_mfma_f32_16x16x32_bf16 v[104:107], v[172:175], v[180:183], v[104:107]
	v_mfma_f32_16x16x32_bf16 v[124:127], v[148:151], v[184:187], v[124:127]
	v_mfma_f32_16x16x32_bf16 v[116:119], v[148:151], v[192:195], v[116:119]
	v_mfma_f32_16x16x32_bf16 v[100:103], v[148:151], v[200:203], v[100:103]
	v_mfma_f32_16x16x32_bf16 v[84:87], v[148:151], v[212:215], v[84:87]
	v_mfma_f32_16x16x32_bf16 v[80:83], v[156:159], v[212:215], v[80:83]
	v_mfma_f32_16x16x32_bf16 v[96:99], v[156:159], v[200:203], v[96:99]
	v_mfma_f32_16x16x32_bf16 v[112:115], v[156:159], v[192:195], v[112:115]
	v_mfma_f32_16x16x32_bf16 v[120:123], v[156:159], v[184:187], v[120:123]
	v_mfma_f32_16x16x32_bf16 v[108:111], v[164:167], v[184:187], v[108:111]
	v_mfma_f32_16x16x32_bf16 v[92:95], v[164:167], v[192:195], v[92:95]
	v_mfma_f32_16x16x32_bf16 v[76:79], v[164:167], v[200:203], v[76:79]
	v_mfma_f32_16x16x32_bf16 v[68:71], v[164:167], v[212:215], v[68:71]
	v_mfma_f32_16x16x32_bf16 v[64:67], v[176:179], v[212:215], v[64:67]
	v_mfma_f32_16x16x32_bf16 v[72:75], v[176:179], v[200:203], v[72:75]
	v_mfma_f32_16x16x32_bf16 v[88:91], v[176:179], v[192:195], v[88:91]
	v_mfma_f32_16x16x32_bf16 v[104:107], v[176:179], v[184:187], v[104:107]
	s_barrier
	s_add_i32 s56, s56, s38
	v_lshl_add_u64 v[218:219], v[208:209], 0, s[12:13]
	s_mov_b32 m0, s56
	s_nop 0
	global_load_lds_dwordx4 v[218:219], off
	v_lshl_add_u64 v[218:219], v[208:209], 0, s[14:15]
	s_add_i32 m0, s56, 0x2000
	s_add_i32 s56, s57, s38
	global_load_lds_dwordx4 v[218:219], off
	v_lshl_add_u64 v[218:219], v[208:209], 0, s[16:17]
	s_mov_b32 m0, s56
	v_lshl_add_u64 v[208:209], v[208:209], 0, s[18:19]
	global_load_lds_dwordx4 v[218:219], off
	s_add_i32 m0, s56, 0x2000
	s_nop 0
	global_load_lds_dwordx4 v[208:209], off
	v_lshl_add_u64 v[208:209], v[216:217], 0, s[12:13]
	s_mov_b32 m0, s44
	s_nop 0
	global_load_lds_dwordx4 v[208:209], off
	v_lshl_add_u64 v[208:209], v[216:217], 0, s[14:15]
	s_mov_b32 m0, s45
	s_nop 0
	global_load_lds_dwordx4 v[208:209], off
	ds_read_b128 v[180:183], v142 offset:49152
	ds_read_b128 v[184:187], v142 offset:50176
	ds_read_b128 v[188:191], v142 offset:51200
	ds_read_b128 v[192:195], v142 offset:52224
	ds_read_b128 v[196:199], v142 offset:53248
	ds_read_b128 v[200:203], v142 offset:54272
	ds_read_b128 v[204:207], v142 offset:55296
	ds_read_b128 v[212:215], v142 offset:56320
	s_waitcnt vmcnt(8)
	s_waitcnt lgkmcnt(0)
	s_barrier
	s_waitcnt lgkmcnt(0)
	v_mfma_f32_16x16x32_bf16 v[60:63], v[144:147], v[180:183], v[60:63]
	v_mfma_f32_16x16x32_bf16 v[52:55], v[144:147], v[188:191], v[52:55]
	v_mfma_f32_16x16x32_bf16 v[36:39], v[144:147], v[196:199], v[36:39]
	v_mfma_f32_16x16x32_bf16 v[20:23], v[144:147], v[204:207], v[20:23]
	v_mfma_f32_16x16x32_bf16 v[16:19], v[152:155], v[204:207], v[16:19]
	v_mfma_f32_16x16x32_bf16 v[32:35], v[152:155], v[196:199], v[32:35]
	v_mfma_f32_16x16x32_bf16 v[48:51], v[152:155], v[188:191], v[48:51]
	v_mfma_f32_16x16x32_bf16 v[56:59], v[152:155], v[180:183], v[56:59]
	v_mfma_f32_16x16x32_bf16 v[44:47], v[160:163], v[180:183], v[44:47]
	v_mfma_f32_16x16x32_bf16 v[28:31], v[160:163], v[188:191], v[28:31]
	v_mfma_f32_16x16x32_bf16 v[12:15], v[160:163], v[196:199], v[12:15]
	v_mfma_f32_16x16x32_bf16 v[4:7], v[160:163], v[204:207], v[4:7]
	v_mfma_f32_16x16x32_bf16 v[0:3], v[172:175], v[204:207], v[0:3]
	v_mfma_f32_16x16x32_bf16 v[8:11], v[172:175], v[196:199], v[8:11]
	v_mfma_f32_16x16x32_bf16 v[24:27], v[172:175], v[188:191], v[24:27]
	v_mfma_f32_16x16x32_bf16 v[40:43], v[172:175], v[180:183], v[40:43]
	v_mfma_f32_16x16x32_bf16 v[60:63], v[148:151], v[184:187], v[60:63]
	v_mfma_f32_16x16x32_bf16 v[52:55], v[148:151], v[192:195], v[52:55]
	v_mfma_f32_16x16x32_bf16 v[36:39], v[148:151], v[200:203], v[36:39]
	v_mfma_f32_16x16x32_bf16 v[20:23], v[148:151], v[212:215], v[20:23]
	v_mfma_f32_16x16x32_bf16 v[16:19], v[156:159], v[212:215], v[16:19]
	v_mfma_f32_16x16x32_bf16 v[32:35], v[156:159], v[200:203], v[32:35]
	v_mfma_f32_16x16x32_bf16 v[48:51], v[156:159], v[192:195], v[48:51]
	v_mfma_f32_16x16x32_bf16 v[56:59], v[156:159], v[184:187], v[56:59]
	v_mfma_f32_16x16x32_bf16 v[44:47], v[164:167], v[184:187], v[44:47]
	v_mfma_f32_16x16x32_bf16 v[28:31], v[164:167], v[192:195], v[28:31]
	v_mfma_f32_16x16x32_bf16 v[12:15], v[164:167], v[200:203], v[12:15]
	v_mfma_f32_16x16x32_bf16 v[4:7], v[164:167], v[212:215], v[4:7]
	v_mfma_f32_16x16x32_bf16 v[0:3], v[176:179], v[212:215], v[0:3]
	v_mfma_f32_16x16x32_bf16 v[8:11], v[176:179], v[200:203], v[8:11]
	v_mfma_f32_16x16x32_bf16 v[24:27], v[176:179], v[192:195], v[24:27]
	v_mfma_f32_16x16x32_bf16 v[40:43], v[176:179], v[184:187], v[40:43]
	s_barrier
	s_cmp_gt_u32 s55, 41
	s_cbranch_scc0 .LBB0_1046
	s_and_b64 vcc, exec, s[20:21]
	s_cbranch_vccz .LBB0_1049
	s_barrier
